# speedup vs baseline: 1.0735x; 1.0004x over previous
;     ...
;     for (int ms = 0; ms < 8; ++ms) {
;       asm volatile("" ::: "memory");
; #pragma unroll
;       for (int ns = 0; ns < 4; ++ns)
; #pragma unroll
;         for (int j = 0; j < 4; ++j) {
;           int row = m0 + wm * 128 + ms * 16 + quad * 4 + j;
;           int col = n0 + wn * 64 + ns * 16 + l15;
;           const size_t xi = (size_t)row * D + col;
;           const float xv = xin ? xin[xi] : P.out[xi];
;           P.out[xi] = alpha * xv + sc * acc[ms][ns][j];
;         }
.LBB0_105:
	v_add_u32_e32 v136, s12, v207
	v_lshl_or_b32 v130, s13, 7, v239
	v_lshlrev_b32_e32 v136, 12, v136
	v_lshl_add_u32 v138, v130, 2, v136
	v_add_u32_e32 v138, 0x1000, v138
	s_and_b64 vcc, exec, s[8:9]
	v_mov_b32_e32 v130, v138
	v_add_u32_e32 v131, 0x2000, v130
	global_load_dword v140, v130, s[86:87] offset:-4096
	global_load_dword v141, v130, s[86:87] offset:-4032
	global_load_dword v142, v130, s[86:87] offset:-3968
	global_load_dword v143, v130, s[86:87] offset:-3904
	global_load_dword v144, v130, s[86:87]
	global_load_dword v145, v130, s[86:87] offset:64
	global_load_dword v146, v130, s[86:87] offset:128
	global_load_dword v147, v130, s[86:87] offset:192
	global_load_dword v148, v131, s[86:87] offset:-4096
	global_load_dword v149, v131, s[86:87] offset:-4032
	global_load_dword v150, v131, s[86:87] offset:-3968
	global_load_dword v151, v131, s[86:87] offset:-3904
	global_load_dword v152, v131, s[86:87]
	global_load_dword v153, v131, s[86:87] offset:64
	global_load_dword v154, v131, s[86:87] offset:128
	global_load_dword v155, v131, s[86:87] offset:192
	v_add_u32_e32 v132, 0x10000, v138
	v_add_u32_e32 v133, 0x2000, v132
	global_load_dword v156, v132, s[86:87] offset:-4096
	global_load_dword v157, v132, s[86:87] offset:-4032
	global_load_dword v158, v132, s[86:87] offset:-3968
	global_load_dword v159, v132, s[86:87] offset:-3904
	global_load_dword v160, v132, s[86:87]
	global_load_dword v161, v132, s[86:87] offset:64
	global_load_dword v162, v132, s[86:87] offset:128
	global_load_dword v163, v132, s[86:87] offset:192
	global_load_dword v164, v133, s[86:87] offset:-4096
	global_load_dword v165, v133, s[86:87] offset:-4032
	global_load_dword v166, v133, s[86:87] offset:-3968
	global_load_dword v167, v133, s[86:87] offset:-3904
	global_load_dword v168, v133, s[86:87]
	global_load_dword v169, v133, s[86:87] offset:64
	global_load_dword v170, v133, s[86:87] offset:128
	global_load_dword v171, v133, s[86:87] offset:192
	s_waitcnt vmcnt(16)
	v_mul_f32_e32 v140, v212, v140
	v_fmac_f32_e32 v140, v211, v126
	global_store_dword v130, v140, s[86:87] offset:-4096
	v_mul_f32_e32 v141, v212, v141
	v_fmac_f32_e32 v141, v211, v122
	global_store_dword v130, v141, s[86:87] offset:-4032
	v_mul_f32_e32 v142, v212, v142
	v_fmac_f32_e32 v142, v211, v118
	global_store_dword v130, v142, s[86:87] offset:-3968
	v_mul_f32_e32 v143, v212, v143
	v_fmac_f32_e32 v143, v211, v114
	global_store_dword v130, v143, s[86:87] offset:-3904
	v_mul_f32_e32 v144, v212, v144
	v_fmac_f32_e32 v144, v211, v127
	global_store_dword v130, v144, s[86:87]
	v_mul_f32_e32 v145, v212, v145
	v_fmac_f32_e32 v145, v211, v123
	global_store_dword v130, v145, s[86:87] offset:64
	v_mul_f32_e32 v146, v212, v146
	v_fmac_f32_e32 v146, v211, v119
	global_store_dword v130, v146, s[86:87] offset:128
	v_mul_f32_e32 v147, v212, v147
	v_fmac_f32_e32 v147, v211, v115
	global_store_dword v130, v147, s[86:87] offset:192
	v_mul_f32_e32 v148, v212, v148
	v_fmac_f32_e32 v148, v211, v128
	global_store_dword v131, v148, s[86:87] offset:-4096
	v_mul_f32_e32 v149, v212, v149
	v_fmac_f32_e32 v149, v211, v124
	global_store_dword v131, v149, s[86:87] offset:-4032
	v_mul_f32_e32 v150, v212, v150
	v_fmac_f32_e32 v150, v211, v120
	global_store_dword v131, v150, s[86:87] offset:-3968
	v_mul_f32_e32 v151, v212, v151
	v_fmac_f32_e32 v151, v211, v116
	global_store_dword v131, v151, s[86:87] offset:-3904
	v_mul_f32_e32 v152, v212, v152
	v_fmac_f32_e32 v152, v211, v129
	global_store_dword v131, v152, s[86:87]
	v_mul_f32_e32 v153, v212, v153
	v_fmac_f32_e32 v153, v211, v125
	global_store_dword v131, v153, s[86:87] offset:64
	v_mul_f32_e32 v154, v212, v154
	v_fmac_f32_e32 v154, v211, v121
	global_store_dword v131, v154, s[86:87] offset:128
	v_mul_f32_e32 v155, v212, v155
	v_fmac_f32_e32 v155, v211, v117
	global_store_dword v131, v155, s[86:87] offset:192
	v_add_u32_e32 v130, 0x20000, v138
	v_add_u32_e32 v131, 0x2000, v130
	global_load_dword v140, v130, s[86:87] offset:-4096
	global_load_dword v141, v130, s[86:87] offset:-4032
	global_load_dword v142, v130, s[86:87] offset:-3968
	global_load_dword v143, v130, s[86:87] offset:-3904
	global_load_dword v144, v130, s[86:87]
	global_load_dword v145, v130, s[86:87] offset:64
	global_load_dword v146, v130, s[86:87] offset:128
	global_load_dword v147, v130, s[86:87] offset:192
	global_load_dword v148, v131, s[86:87] offset:-4096
	global_load_dword v149, v131, s[86:87] offset:-4032
	global_load_dword v150, v131, s[86:87] offset:-3968
	global_load_dword v151, v131, s[86:87] offset:-3904
	global_load_dword v152, v131, s[86:87]
	global_load_dword v153, v131, s[86:87] offset:64
	global_load_dword v154, v131, s[86:87] offset:128
	global_load_dword v155, v131, s[86:87] offset:192
	s_waitcnt vmcnt(32)
;     ...
;     for (int ms = 0; ms < 8; ++ms) {
;       asm volatile("" ::: "memory");
; #pragma unroll
;       for (int ns = 0; ns < 4; ++ns)
; #pragma unroll
;         for (int j = 0; j < 4; ++j) {
;           int row = m0 + wm * 128 + ms * 16 + quad * 4 + j;
;           int col = n0 + wn * 64 + ns * 16 + l15;
;           const size_t xi = (size_t)row * D + col;
;           const float xv = xin ? xin[xi] : P.out[xi];
;           P.out[xi] = alpha * xv + sc * acc[ms][ns][j];
;         }
	v_mul_f32_e32 v156, v212, v156
	v_fmac_f32_e32 v156, v211, v110
	global_store_dword v132, v156, s[86:87] offset:-4096
	v_mul_f32_e32 v157, v212, v157
	v_fmac_f32_e32 v157, v211, v106
	global_store_dword v132, v157, s[86:87] offset:-4032
	v_mul_f32_e32 v158, v212, v158
	v_fmac_f32_e32 v158, v211, v102
	global_store_dword v132, v158, s[86:87] offset:-3968
	v_mul_f32_e32 v159, v212, v159
	v_fmac_f32_e32 v159, v211, v98
	global_store_dword v132, v159, s[86:87] offset:-3904
	v_mul_f32_e32 v160, v212, v160
	v_fmac_f32_e32 v160, v211, v111
	global_store_dword v132, v160, s[86:87]
	v_mul_f32_e32 v161, v212, v161
	v_fmac_f32_e32 v161, v211, v107
	global_store_dword v132, v161, s[86:87] offset:64
	v_mul_f32_e32 v162, v212, v162
	v_fmac_f32_e32 v162, v211, v103
	global_store_dword v132, v162, s[86:87] offset:128
	v_mul_f32_e32 v163, v212, v163
	v_fmac_f32_e32 v163, v211, v99
	global_store_dword v132, v163, s[86:87] offset:192
	v_mul_f32_e32 v164, v212, v164
	v_fmac_f32_e32 v164, v211, v112
	global_store_dword v133, v164, s[86:87] offset:-4096
	v_mul_f32_e32 v165, v212, v165
	v_fmac_f32_e32 v165, v211, v108
	global_store_dword v133, v165, s[86:87] offset:-4032
	v_mul_f32_e32 v166, v212, v166
	v_fmac_f32_e32 v166, v211, v104
	global_store_dword v133, v166, s[86:87] offset:-3968
	v_mul_f32_e32 v167, v212, v167
	v_fmac_f32_e32 v167, v211, v100
	global_store_dword v133, v167, s[86:87] offset:-3904
	v_mul_f32_e32 v168, v212, v168
	v_fmac_f32_e32 v168, v211, v113
	global_store_dword v133, v168, s[86:87]
	v_mul_f32_e32 v169, v212, v169
	v_fmac_f32_e32 v169, v211, v109
	global_store_dword v133, v169, s[86:87] offset:64
	v_mul_f32_e32 v170, v212, v170
	v_fmac_f32_e32 v170, v211, v105
	global_store_dword v133, v170, s[86:87] offset:128
	v_mul_f32_e32 v171, v212, v171
	v_fmac_f32_e32 v171, v211, v101
	global_store_dword v133, v171, s[86:87] offset:192
	v_add_u32_e32 v132, 0x30000, v138
	v_add_u32_e32 v133, 0x2000, v132
	global_load_dword v156, v132, s[86:87] offset:-4096
	global_load_dword v157, v132, s[86:87] offset:-4032
	global_load_dword v158, v132, s[86:87] offset:-3968
	global_load_dword v159, v132, s[86:87] offset:-3904
	global_load_dword v160, v132, s[86:87]
	global_load_dword v161, v132, s[86:87] offset:64
	global_load_dword v162, v132, s[86:87] offset:128
	global_load_dword v163, v132, s[86:87] offset:192
	global_load_dword v164, v133, s[86:87] offset:-4096
	global_load_dword v165, v133, s[86:87] offset:-4032
	global_load_dword v166, v133, s[86:87] offset:-3968
	global_load_dword v167, v133, s[86:87] offset:-3904
	global_load_dword v168, v133, s[86:87]
	global_load_dword v169, v133, s[86:87] offset:64
	global_load_dword v170, v133, s[86:87] offset:128
	global_load_dword v171, v133, s[86:87] offset:192
	s_waitcnt vmcnt(32)
	v_mul_f32_e32 v140, v212, v140
	v_fmac_f32_e32 v140, v211, v94
	global_store_dword v130, v140, s[86:87] offset:-4096
	v_mul_f32_e32 v141, v212, v141
	v_fmac_f32_e32 v141, v211, v90
	global_store_dword v130, v141, s[86:87] offset:-4032
	v_mul_f32_e32 v142, v212, v142
	v_fmac_f32_e32 v142, v211, v86
	global_store_dword v130, v142, s[86:87] offset:-3968
	v_mul_f32_e32 v143, v212, v143
	v_fmac_f32_e32 v143, v211, v82
	global_store_dword v130, v143, s[86:87] offset:-3904
	v_mul_f32_e32 v144, v212, v144
	v_fmac_f32_e32 v144, v211, v95
	global_store_dword v130, v144, s[86:87]
	v_mul_f32_e32 v145, v212, v145
	v_fmac_f32_e32 v145, v211, v91
	global_store_dword v130, v145, s[86:87] offset:64
	v_mul_f32_e32 v146, v212, v146
	v_fmac_f32_e32 v146, v211, v87
	global_store_dword v130, v146, s[86:87] offset:128
	v_mul_f32_e32 v147, v212, v147
	v_fmac_f32_e32 v147, v211, v83
	global_store_dword v130, v147, s[86:87] offset:192
	v_mul_f32_e32 v148, v212, v148
	v_fmac_f32_e32 v148, v211, v96
	global_store_dword v131, v148, s[86:87] offset:-4096
	v_mul_f32_e32 v149, v212, v149
	v_fmac_f32_e32 v149, v211, v92
	global_store_dword v131, v149, s[86:87] offset:-4032
	v_mul_f32_e32 v150, v212, v150
	v_fmac_f32_e32 v150, v211, v88
	global_store_dword v131, v150, s[86:87] offset:-3968
	v_mul_f32_e32 v151, v212, v151
	v_fmac_f32_e32 v151, v211, v84
	global_store_dword v131, v151, s[86:87] offset:-3904
	v_mul_f32_e32 v152, v212, v152
	v_fmac_f32_e32 v152, v211, v97
	global_store_dword v131, v152, s[86:87]
	v_mul_f32_e32 v153, v212, v153
	v_fmac_f32_e32 v153, v211, v93
	global_store_dword v131, v153, s[86:87] offset:64
	v_mul_f32_e32 v154, v212, v154
	v_fmac_f32_e32 v154, v211, v89
	global_store_dword v131, v154, s[86:87] offset:128
	v_mul_f32_e32 v155, v212, v155
	v_fmac_f32_e32 v155, v211, v85
	global_store_dword v131, v155, s[86:87] offset:192
	v_add_u32_e32 v130, 0x40000, v138
	v_add_u32_e32 v131, 0x2000, v130
	global_load_dword v140, v130, s[86:87] offset:-4096
	global_load_dword v141, v130, s[86:87] offset:-4032
	global_load_dword v142, v130, s[86:87] offset:-3968
	global_load_dword v143, v130, s[86:87] offset:-3904
	global_load_dword v144, v130, s[86:87]
	global_load_dword v145, v130, s[86:87] offset:64
	global_load_dword v146, v130, s[86:87] offset:128
	global_load_dword v147, v130, s[86:87] offset:192
	global_load_dword v148, v131, s[86:87] offset:-4096
	global_load_dword v149, v131, s[86:87] offset:-4032
	global_load_dword v150, v131, s[86:87] offset:-3968
	global_load_dword v151, v131, s[86:87] offset:-3904
	global_load_dword v152, v131, s[86:87]
	global_load_dword v153, v131, s[86:87] offset:64
	global_load_dword v154, v131, s[86:87] offset:128
	global_load_dword v155, v131, s[86:87] offset:192
	s_waitcnt vmcnt(32)
;     ...
;     for (int ms = 0; ms < 8; ++ms) {
;       asm volatile("" ::: "memory");
; #pragma unroll
;       for (int ns = 0; ns < 4; ++ns)
; #pragma unroll
;         for (int j = 0; j < 4; ++j) {
;           int row = m0 + wm * 128 + ms * 16 + quad * 4 + j;
;           int col = n0 + wn * 64 + ns * 16 + l15;
;           const size_t xi = (size_t)row * D + col;
;           const float xv = xin ? xin[xi] : P.out[xi];
;           P.out[xi] = alpha * xv + sc * acc[ms][ns][j];
;         }
	v_mul_f32_e32 v156, v212, v156
	v_fmac_f32_e32 v156, v211, v78
	global_store_dword v132, v156, s[86:87] offset:-4096
	v_mul_f32_e32 v157, v212, v157
	v_fmac_f32_e32 v157, v211, v74
	global_store_dword v132, v157, s[86:87] offset:-4032
	v_mul_f32_e32 v158, v212, v158
	v_fmac_f32_e32 v158, v211, v70
	global_store_dword v132, v158, s[86:87] offset:-3968
	v_mul_f32_e32 v159, v212, v159
	v_fmac_f32_e32 v159, v211, v66
	global_store_dword v132, v159, s[86:87] offset:-3904
	v_mul_f32_e32 v160, v212, v160
	v_fmac_f32_e32 v160, v211, v79
	global_store_dword v132, v160, s[86:87]
	v_mul_f32_e32 v161, v212, v161
	v_fmac_f32_e32 v161, v211, v75
	global_store_dword v132, v161, s[86:87] offset:64
	v_mul_f32_e32 v162, v212, v162
	v_fmac_f32_e32 v162, v211, v71
	global_store_dword v132, v162, s[86:87] offset:128
	v_mul_f32_e32 v163, v212, v163
	v_fmac_f32_e32 v163, v211, v67
	global_store_dword v132, v163, s[86:87] offset:192
	v_mul_f32_e32 v164, v212, v164
	v_fmac_f32_e32 v164, v211, v80
	global_store_dword v133, v164, s[86:87] offset:-4096
	v_mul_f32_e32 v165, v212, v165
	v_fmac_f32_e32 v165, v211, v76
	global_store_dword v133, v165, s[86:87] offset:-4032
	v_mul_f32_e32 v166, v212, v166
	v_fmac_f32_e32 v166, v211, v72
	global_store_dword v133, v166, s[86:87] offset:-3968
	v_mul_f32_e32 v167, v212, v167
	v_fmac_f32_e32 v167, v211, v68
	global_store_dword v133, v167, s[86:87] offset:-3904
	v_mul_f32_e32 v168, v212, v168
	v_fmac_f32_e32 v168, v211, v81
	global_store_dword v133, v168, s[86:87]
	v_mul_f32_e32 v169, v212, v169
	v_fmac_f32_e32 v169, v211, v77
	global_store_dword v133, v169, s[86:87] offset:64
	v_mul_f32_e32 v170, v212, v170
	v_fmac_f32_e32 v170, v211, v73
	global_store_dword v133, v170, s[86:87] offset:128
	v_mul_f32_e32 v171, v212, v171
	v_fmac_f32_e32 v171, v211, v69
	global_store_dword v133, v171, s[86:87] offset:192
	v_add_u32_e32 v132, 0x50000, v138
	v_add_u32_e32 v133, 0x2000, v132
	global_load_dword v156, v132, s[86:87] offset:-4096
	global_load_dword v157, v132, s[86:87] offset:-4032
	global_load_dword v158, v132, s[86:87] offset:-3968
	global_load_dword v159, v132, s[86:87] offset:-3904
	global_load_dword v160, v132, s[86:87]
	global_load_dword v161, v132, s[86:87] offset:64
	global_load_dword v162, v132, s[86:87] offset:128
	global_load_dword v163, v132, s[86:87] offset:192
	global_load_dword v164, v133, s[86:87] offset:-4096
	global_load_dword v165, v133, s[86:87] offset:-4032
	global_load_dword v166, v133, s[86:87] offset:-3968
	global_load_dword v167, v133, s[86:87] offset:-3904
	global_load_dword v168, v133, s[86:87]
	global_load_dword v169, v133, s[86:87] offset:64
	global_load_dword v170, v133, s[86:87] offset:128
	global_load_dword v171, v133, s[86:87] offset:192
	s_waitcnt vmcnt(32)
	v_mul_f32_e32 v140, v212, v140
	v_fmac_f32_e32 v140, v211, v62
	global_store_dword v130, v140, s[86:87] offset:-4096
	v_mul_f32_e32 v141, v212, v141
	v_fmac_f32_e32 v141, v211, v58
	global_store_dword v130, v141, s[86:87] offset:-4032
	v_mul_f32_e32 v142, v212, v142
	v_fmac_f32_e32 v142, v211, v54
	global_store_dword v130, v142, s[86:87] offset:-3968
	v_mul_f32_e32 v143, v212, v143
	v_fmac_f32_e32 v143, v211, v50
	global_store_dword v130, v143, s[86:87] offset:-3904
	v_mul_f32_e32 v144, v212, v144
	v_fmac_f32_e32 v144, v211, v63
	global_store_dword v130, v144, s[86:87]
	v_mul_f32_e32 v145, v212, v145
	v_fmac_f32_e32 v145, v211, v59
	global_store_dword v130, v145, s[86:87] offset:64
	v_mul_f32_e32 v146, v212, v146
	v_fmac_f32_e32 v146, v211, v55
	global_store_dword v130, v146, s[86:87] offset:128
	v_mul_f32_e32 v147, v212, v147
	v_fmac_f32_e32 v147, v211, v51
	global_store_dword v130, v147, s[86:87] offset:192
	v_mul_f32_e32 v148, v212, v148
	v_fmac_f32_e32 v148, v211, v64
	global_store_dword v131, v148, s[86:87] offset:-4096
	v_mul_f32_e32 v149, v212, v149
	v_fmac_f32_e32 v149, v211, v60
	global_store_dword v131, v149, s[86:87] offset:-4032
	v_mul_f32_e32 v150, v212, v150
	v_fmac_f32_e32 v150, v211, v56
	global_store_dword v131, v150, s[86:87] offset:-3968
	v_mul_f32_e32 v151, v212, v151
	v_fmac_f32_e32 v151, v211, v52
	global_store_dword v131, v151, s[86:87] offset:-3904
	v_mul_f32_e32 v152, v212, v152
	v_fmac_f32_e32 v152, v211, v65
	global_store_dword v131, v152, s[86:87]
	v_mul_f32_e32 v153, v212, v153
	v_fmac_f32_e32 v153, v211, v61
	global_store_dword v131, v153, s[86:87] offset:64
	v_mul_f32_e32 v154, v212, v154
	v_fmac_f32_e32 v154, v211, v57
	global_store_dword v131, v154, s[86:87] offset:128
	v_mul_f32_e32 v155, v212, v155
	v_fmac_f32_e32 v155, v211, v53
	global_store_dword v131, v155, s[86:87] offset:192
	v_add_u32_e32 v130, 0x60000, v138
	v_add_u32_e32 v131, 0x2000, v130
	global_load_dword v140, v130, s[86:87] offset:-4096
	global_load_dword v141, v130, s[86:87] offset:-4032
	global_load_dword v142, v130, s[86:87] offset:-3968
	global_load_dword v143, v130, s[86:87] offset:-3904
	global_load_dword v144, v130, s[86:87]
	global_load_dword v145, v130, s[86:87] offset:64
	global_load_dword v146, v130, s[86:87] offset:128
	global_load_dword v147, v130, s[86:87] offset:192
	global_load_dword v148, v131, s[86:87] offset:-4096
	global_load_dword v149, v131, s[86:87] offset:-4032
	global_load_dword v150, v131, s[86:87] offset:-3968
	global_load_dword v151, v131, s[86:87] offset:-3904
	global_load_dword v152, v131, s[86:87]
	global_load_dword v153, v131, s[86:87] offset:64
	global_load_dword v154, v131, s[86:87] offset:128
	global_load_dword v155, v131, s[86:87] offset:192
	s_waitcnt vmcnt(32)
;     ...
;     for (int ms = 0; ms < 8; ++ms) {
;       asm volatile("" ::: "memory");
; #pragma unroll
;       for (int ns = 0; ns < 4; ++ns)
; #pragma unroll
;         for (int j = 0; j < 4; ++j) {
;           int row = m0 + wm * 128 + ms * 16 + quad * 4 + j;
;           int col = n0 + wn * 64 + ns * 16 + l15;
;           const size_t xi = (size_t)row * D + col;
;           const float xv = xin ? xin[xi] : P.out[xi];
;           P.out[xi] = alpha * xv + sc * acc[ms][ns][j];
;         }
	v_mul_f32_e32 v156, v212, v156
	v_fmac_f32_e32 v156, v211, v46
	global_store_dword v132, v156, s[86:87] offset:-4096
	v_mul_f32_e32 v157, v212, v157
	v_fmac_f32_e32 v157, v211, v42
	global_store_dword v132, v157, s[86:87] offset:-4032
	v_mul_f32_e32 v158, v212, v158
	v_fmac_f32_e32 v158, v211, v38
	global_store_dword v132, v158, s[86:87] offset:-3968
	v_mul_f32_e32 v159, v212, v159
	v_fmac_f32_e32 v159, v211, v34
	global_store_dword v132, v159, s[86:87] offset:-3904
	v_mul_f32_e32 v160, v212, v160
	v_fmac_f32_e32 v160, v211, v47
	global_store_dword v132, v160, s[86:87]
	v_mul_f32_e32 v161, v212, v161
	v_fmac_f32_e32 v161, v211, v43
	global_store_dword v132, v161, s[86:87] offset:64
	v_mul_f32_e32 v162, v212, v162
	v_fmac_f32_e32 v162, v211, v39
	global_store_dword v132, v162, s[86:87] offset:128
	v_mul_f32_e32 v163, v212, v163
	v_fmac_f32_e32 v163, v211, v35
	global_store_dword v132, v163, s[86:87] offset:192
	v_mul_f32_e32 v164, v212, v164
	v_fmac_f32_e32 v164, v211, v48
	global_store_dword v133, v164, s[86:87] offset:-4096
	v_mul_f32_e32 v165, v212, v165
	v_fmac_f32_e32 v165, v211, v44
	global_store_dword v133, v165, s[86:87] offset:-4032
	v_mul_f32_e32 v166, v212, v166
	v_fmac_f32_e32 v166, v211, v40
	global_store_dword v133, v166, s[86:87] offset:-3968
	v_mul_f32_e32 v167, v212, v167
	v_fmac_f32_e32 v167, v211, v36
	global_store_dword v133, v167, s[86:87] offset:-3904
	v_mul_f32_e32 v168, v212, v168
	v_fmac_f32_e32 v168, v211, v49
	global_store_dword v133, v168, s[86:87]
	v_mul_f32_e32 v169, v212, v169
	v_fmac_f32_e32 v169, v211, v45
	global_store_dword v133, v169, s[86:87] offset:64
	v_mul_f32_e32 v170, v212, v170
	v_fmac_f32_e32 v170, v211, v41
	global_store_dword v133, v170, s[86:87] offset:128
	v_mul_f32_e32 v171, v212, v171
	v_fmac_f32_e32 v171, v211, v37
	global_store_dword v133, v171, s[86:87] offset:192
	v_add_u32_e32 v132, 0x70000, v138
	v_add_u32_e32 v133, 0x2000, v132
	global_load_dword v156, v132, s[86:87] offset:-4096
	global_load_dword v157, v132, s[86:87] offset:-4032
	global_load_dword v158, v132, s[86:87] offset:-3968
	global_load_dword v159, v132, s[86:87] offset:-3904
	global_load_dword v160, v132, s[86:87]
	global_load_dword v161, v132, s[86:87] offset:64
	global_load_dword v162, v132, s[86:87] offset:128
	global_load_dword v163, v132, s[86:87] offset:192
	global_load_dword v164, v133, s[86:87] offset:-4096
	global_load_dword v165, v133, s[86:87] offset:-4032
	global_load_dword v166, v133, s[86:87] offset:-3968
	global_load_dword v167, v133, s[86:87] offset:-3904
	global_load_dword v168, v133, s[86:87]
	global_load_dword v169, v133, s[86:87] offset:64
	global_load_dword v170, v133, s[86:87] offset:128
	global_load_dword v171, v133, s[86:87] offset:192
	s_waitcnt vmcnt(32)
	v_mul_f32_e32 v140, v212, v140
	v_fmac_f32_e32 v140, v211, v30
	global_store_dword v130, v140, s[86:87] offset:-4096
	v_mul_f32_e32 v141, v212, v141
	v_fmac_f32_e32 v141, v211, v26
	global_store_dword v130, v141, s[86:87] offset:-4032
	v_mul_f32_e32 v142, v212, v142
	v_fmac_f32_e32 v142, v211, v22
	global_store_dword v130, v142, s[86:87] offset:-3968
	v_mul_f32_e32 v143, v212, v143
	v_fmac_f32_e32 v143, v211, v18
	global_store_dword v130, v143, s[86:87] offset:-3904
	v_mul_f32_e32 v144, v212, v144
	v_fmac_f32_e32 v144, v211, v31
	global_store_dword v130, v144, s[86:87]
	v_mul_f32_e32 v145, v212, v145
	v_fmac_f32_e32 v145, v211, v27
	global_store_dword v130, v145, s[86:87] offset:64
	v_mul_f32_e32 v146, v212, v146
	v_fmac_f32_e32 v146, v211, v23
	global_store_dword v130, v146, s[86:87] offset:128
	v_mul_f32_e32 v147, v212, v147
	v_fmac_f32_e32 v147, v211, v19
	global_store_dword v130, v147, s[86:87] offset:192
	v_mul_f32_e32 v148, v212, v148
	v_fmac_f32_e32 v148, v211, v32
	global_store_dword v131, v148, s[86:87] offset:-4096
	v_mul_f32_e32 v149, v212, v149
	v_fmac_f32_e32 v149, v211, v28
	global_store_dword v131, v149, s[86:87] offset:-4032
	v_mul_f32_e32 v150, v212, v150
	v_fmac_f32_e32 v150, v211, v24
	global_store_dword v131, v150, s[86:87] offset:-3968
	v_mul_f32_e32 v151, v212, v151
	v_fmac_f32_e32 v151, v211, v20
	global_store_dword v131, v151, s[86:87] offset:-3904
	v_mul_f32_e32 v152, v212, v152
	v_fmac_f32_e32 v152, v211, v33
	global_store_dword v131, v152, s[86:87]
	v_mul_f32_e32 v153, v212, v153
	v_fmac_f32_e32 v153, v211, v29
	global_store_dword v131, v153, s[86:87] offset:64
	v_mul_f32_e32 v154, v212, v154
	v_fmac_f32_e32 v154, v211, v25
	global_store_dword v131, v154, s[86:87] offset:128
	v_mul_f32_e32 v155, v212, v155
	v_fmac_f32_e32 v155, v211, v21
	global_store_dword v131, v155, s[86:87] offset:192
	s_waitcnt vmcnt(16)
	v_mul_f32_e32 v156, v212, v156
	v_fmac_f32_e32 v156, v211, v14
	global_store_dword v132, v156, s[86:87] offset:-4096
	v_mul_f32_e32 v157, v212, v157
	v_fmac_f32_e32 v157, v211, v10
	global_store_dword v132, v157, s[86:87] offset:-4032
	v_mul_f32_e32 v158, v212, v158
	v_fmac_f32_e32 v158, v211, v6
	global_store_dword v132, v158, s[86:87] offset:-3968
	v_mul_f32_e32 v159, v212, v159
	v_fmac_f32_e32 v159, v211, v2
	global_store_dword v132, v159, s[86:87] offset:-3904
	v_mul_f32_e32 v160, v212, v160
	v_fmac_f32_e32 v160, v211, v15
	global_store_dword v132, v160, s[86:87]
	v_mul_f32_e32 v161, v212, v161
	v_fmac_f32_e32 v161, v211, v11
	global_store_dword v132, v161, s[86:87] offset:64
	v_mul_f32_e32 v162, v212, v162
	v_fmac_f32_e32 v162, v211, v7
	global_store_dword v132, v162, s[86:87] offset:128
	v_mul_f32_e32 v163, v212, v163
	v_fmac_f32_e32 v163, v211, v3
	global_store_dword v132, v163, s[86:87] offset:192
	v_mul_f32_e32 v164, v212, v164
	v_fmac_f32_e32 v164, v211, v16
	global_store_dword v133, v164, s[86:87] offset:-4096
	v_mul_f32_e32 v165, v212, v165
	v_fmac_f32_e32 v165, v211, v12
	global_store_dword v133, v165, s[86:87] offset:-4032
	v_mul_f32_e32 v166, v212, v166
	v_fmac_f32_e32 v166, v211, v8
	global_store_dword v133, v166, s[86:87] offset:-3968
	v_mul_f32_e32 v167, v212, v167
	v_fmac_f32_e32 v167, v211, v4
	global_store_dword v133, v167, s[86:87] offset:-3904
	v_mul_f32_e32 v168, v212, v168
	v_fmac_f32_e32 v168, v211, v17
	global_store_dword v133, v168, s[86:87]
	v_mul_f32_e32 v169, v212, v169
	v_fmac_f32_e32 v169, v211, v13
	global_store_dword v133, v169, s[86:87] offset:64
	v_mul_f32_e32 v170, v212, v170
	v_fmac_f32_e32 v170, v211, v9
	global_store_dword v133, v170, s[86:87] offset:128
	v_mul_f32_e32 v171, v212, v171
	v_fmac_f32_e32 v171, v211, v5
	global_store_dword v133, v171, s[86:87] offset:192
	s_cbranch_vccnz .LBB0_130

;     ...
;     for (int ms = 0; ms < 8; ++ms) {
;       asm volatile("" ::: "memory");
; #pragma unroll
;       for (int ns = 0; ns < 4; ++ns)
; #pragma unroll
;         for (int j = 0; j < 4; ++j) {
;           int row = m0 + wm * 128 + ms * 16 + quad * 4 + j;
;           int col = n0 + wn * 64 + ns * 16 + l15;
;           const size_t xi = (size_t)row * D + col;
;           const float xv = xin ? xin[xi] : P.out[xi];
;           P.out[xi] = alpha * xv + sc * acc[ms][ns][j];
;         }
.LBB0_134:
	v_add_u32_e32 v136, s12, v183
	v_or_b32_e32 v130, s13, v178
	v_lshlrev_b32_e32 v136, 12, v136
	v_lshl_add_u32 v138, v130, 2, v136
	v_add_u32_e32 v138, 0x1000, v138
	s_and_b64 vcc, exec, s[8:9]
	v_mov_b32_e32 v130, v138
	v_add_u32_e32 v131, 0x2000, v130
	global_load_dword v140, v130, s[86:87] offset:-4096
	global_load_dword v141, v130, s[86:87] offset:-4032
	global_load_dword v142, v130, s[86:87] offset:-3968
	global_load_dword v143, v130, s[86:87] offset:-3904
	global_load_dword v144, v130, s[86:87]
	global_load_dword v145, v130, s[86:87] offset:64
	global_load_dword v146, v130, s[86:87] offset:128
	global_load_dword v147, v130, s[86:87] offset:192
	global_load_dword v148, v131, s[86:87] offset:-4096
	global_load_dword v149, v131, s[86:87] offset:-4032
	global_load_dword v150, v131, s[86:87] offset:-3968
	global_load_dword v151, v131, s[86:87] offset:-3904
	global_load_dword v152, v131, s[86:87]
	global_load_dword v153, v131, s[86:87] offset:64
	global_load_dword v154, v131, s[86:87] offset:128
	global_load_dword v155, v131, s[86:87] offset:192
	v_add_u32_e32 v132, 0x10000, v138
	v_add_u32_e32 v133, 0x2000, v132
	global_load_dword v156, v132, s[86:87] offset:-4096
	global_load_dword v157, v132, s[86:87] offset:-4032
	global_load_dword v158, v132, s[86:87] offset:-3968
	global_load_dword v159, v132, s[86:87] offset:-3904
	global_load_dword v160, v132, s[86:87]
	global_load_dword v161, v132, s[86:87] offset:64
	global_load_dword v162, v132, s[86:87] offset:128
	global_load_dword v163, v132, s[86:87] offset:192
	global_load_dword v164, v133, s[86:87] offset:-4096
	global_load_dword v165, v133, s[86:87] offset:-4032
	global_load_dword v166, v133, s[86:87] offset:-3968
	global_load_dword v167, v133, s[86:87] offset:-3904
	global_load_dword v168, v133, s[86:87]
	global_load_dword v169, v133, s[86:87] offset:64
	global_load_dword v170, v133, s[86:87] offset:128
	global_load_dword v171, v133, s[86:87] offset:192
	s_waitcnt vmcnt(16)
	v_mul_f32_e32 v140, v212, v140
	v_fmac_f32_e32 v140, v211, v126
	global_store_dword v130, v140, s[86:87] offset:-4096
	v_mul_f32_e32 v141, v212, v141
	v_fmac_f32_e32 v141, v211, v122
	global_store_dword v130, v141, s[86:87] offset:-4032
	v_mul_f32_e32 v142, v212, v142
	v_fmac_f32_e32 v142, v211, v118
	global_store_dword v130, v142, s[86:87] offset:-3968
	v_mul_f32_e32 v143, v212, v143
	v_fmac_f32_e32 v143, v211, v114
	global_store_dword v130, v143, s[86:87] offset:-3904
	v_mul_f32_e32 v144, v212, v144
	v_fmac_f32_e32 v144, v211, v127
	global_store_dword v130, v144, s[86:87]
	v_mul_f32_e32 v145, v212, v145
	v_fmac_f32_e32 v145, v211, v123
	global_store_dword v130, v145, s[86:87] offset:64
	v_mul_f32_e32 v146, v212, v146
	v_fmac_f32_e32 v146, v211, v119
	global_store_dword v130, v146, s[86:87] offset:128
	v_mul_f32_e32 v147, v212, v147
	v_fmac_f32_e32 v147, v211, v115
	global_store_dword v130, v147, s[86:87] offset:192
	v_mul_f32_e32 v148, v212, v148
	v_fmac_f32_e32 v148, v211, v128
	global_store_dword v131, v148, s[86:87] offset:-4096
	v_mul_f32_e32 v149, v212, v149
	v_fmac_f32_e32 v149, v211, v124
	global_store_dword v131, v149, s[86:87] offset:-4032
	v_mul_f32_e32 v150, v212, v150
	v_fmac_f32_e32 v150, v211, v120
	global_store_dword v131, v150, s[86:87] offset:-3968
	v_mul_f32_e32 v151, v212, v151
	v_fmac_f32_e32 v151, v211, v116
	global_store_dword v131, v151, s[86:87] offset:-3904
	v_mul_f32_e32 v152, v212, v152
	v_fmac_f32_e32 v152, v211, v129
	global_store_dword v131, v152, s[86:87]
	v_mul_f32_e32 v153, v212, v153
	v_fmac_f32_e32 v153, v211, v125
	global_store_dword v131, v153, s[86:87] offset:64
	v_mul_f32_e32 v154, v212, v154
	v_fmac_f32_e32 v154, v211, v121
	global_store_dword v131, v154, s[86:87] offset:128
	v_mul_f32_e32 v155, v212, v155
	v_fmac_f32_e32 v155, v211, v117
	global_store_dword v131, v155, s[86:87] offset:192
	v_add_u32_e32 v130, 0x20000, v138
	v_add_u32_e32 v131, 0x2000, v130
	global_load_dword v140, v130, s[86:87] offset:-4096
	global_load_dword v141, v130, s[86:87] offset:-4032
	global_load_dword v142, v130, s[86:87] offset:-3968
	global_load_dword v143, v130, s[86:87] offset:-3904
	global_load_dword v144, v130, s[86:87]
	global_load_dword v145, v130, s[86:87] offset:64
	global_load_dword v146, v130, s[86:87] offset:128
	global_load_dword v147, v130, s[86:87] offset:192
	global_load_dword v148, v131, s[86:87] offset:-4096
	global_load_dword v149, v131, s[86:87] offset:-4032
	global_load_dword v150, v131, s[86:87] offset:-3968
	global_load_dword v151, v131, s[86:87] offset:-3904
	global_load_dword v152, v131, s[86:87]
	global_load_dword v153, v131, s[86:87] offset:64
	global_load_dword v154, v131, s[86:87] offset:128
	global_load_dword v155, v131, s[86:87] offset:192
	s_waitcnt vmcnt(32)
;     ...
;     for (int ms = 0; ms < 8; ++ms) {
;       asm volatile("" ::: "memory");
; #pragma unroll
;       for (int ns = 0; ns < 4; ++ns)
; #pragma unroll
;         for (int j = 0; j < 4; ++j) {
;           int row = m0 + wm * 128 + ms * 16 + quad * 4 + j;
;           int col = n0 + wn * 64 + ns * 16 + l15;
;           const size_t xi = (size_t)row * D + col;
;           const float xv = xin ? xin[xi] : P.out[xi];
;           P.out[xi] = alpha * xv + sc * acc[ms][ns][j];
;         }
	v_mul_f32_e32 v156, v212, v156
	v_fmac_f32_e32 v156, v211, v110
	global_store_dword v132, v156, s[86:87] offset:-4096
	v_mul_f32_e32 v157, v212, v157
	v_fmac_f32_e32 v157, v211, v106
	global_store_dword v132, v157, s[86:87] offset:-4032
	v_mul_f32_e32 v158, v212, v158
	v_fmac_f32_e32 v158, v211, v102
	global_store_dword v132, v158, s[86:87] offset:-3968
	v_mul_f32_e32 v159, v212, v159
	v_fmac_f32_e32 v159, v211, v98
	global_store_dword v132, v159, s[86:87] offset:-3904
	v_mul_f32_e32 v160, v212, v160
	v_fmac_f32_e32 v160, v211, v111
	global_store_dword v132, v160, s[86:87]
	v_mul_f32_e32 v161, v212, v161
	v_fmac_f32_e32 v161, v211, v107
	global_store_dword v132, v161, s[86:87] offset:64
	v_mul_f32_e32 v162, v212, v162
	v_fmac_f32_e32 v162, v211, v103
	global_store_dword v132, v162, s[86:87] offset:128
	v_mul_f32_e32 v163, v212, v163
	v_fmac_f32_e32 v163, v211, v99
	global_store_dword v132, v163, s[86:87] offset:192
	v_mul_f32_e32 v164, v212, v164
	v_fmac_f32_e32 v164, v211, v112
	global_store_dword v133, v164, s[86:87] offset:-4096
	v_mul_f32_e32 v165, v212, v165
	v_fmac_f32_e32 v165, v211, v108
	global_store_dword v133, v165, s[86:87] offset:-4032
	v_mul_f32_e32 v166, v212, v166
	v_fmac_f32_e32 v166, v211, v104
	global_store_dword v133, v166, s[86:87] offset:-3968
	v_mul_f32_e32 v167, v212, v167
	v_fmac_f32_e32 v167, v211, v100
	global_store_dword v133, v167, s[86:87] offset:-3904
	v_mul_f32_e32 v168, v212, v168
	v_fmac_f32_e32 v168, v211, v113
	global_store_dword v133, v168, s[86:87]
	v_mul_f32_e32 v169, v212, v169
	v_fmac_f32_e32 v169, v211, v109
	global_store_dword v133, v169, s[86:87] offset:64
	v_mul_f32_e32 v170, v212, v170
	v_fmac_f32_e32 v170, v211, v105
	global_store_dword v133, v170, s[86:87] offset:128
	v_mul_f32_e32 v171, v212, v171
	v_fmac_f32_e32 v171, v211, v101
	global_store_dword v133, v171, s[86:87] offset:192
	v_add_u32_e32 v132, 0x30000, v138
	v_add_u32_e32 v133, 0x2000, v132
	global_load_dword v156, v132, s[86:87] offset:-4096
	global_load_dword v157, v132, s[86:87] offset:-4032
	global_load_dword v158, v132, s[86:87] offset:-3968
	global_load_dword v159, v132, s[86:87] offset:-3904
	global_load_dword v160, v132, s[86:87]
	global_load_dword v161, v132, s[86:87] offset:64
	global_load_dword v162, v132, s[86:87] offset:128
	global_load_dword v163, v132, s[86:87] offset:192
	global_load_dword v164, v133, s[86:87] offset:-4096
	global_load_dword v165, v133, s[86:87] offset:-4032
	global_load_dword v166, v133, s[86:87] offset:-3968
	global_load_dword v167, v133, s[86:87] offset:-3904
	global_load_dword v168, v133, s[86:87]
	global_load_dword v169, v133, s[86:87] offset:64
	global_load_dword v170, v133, s[86:87] offset:128
	global_load_dword v171, v133, s[86:87] offset:192
	s_waitcnt vmcnt(32)
	v_mul_f32_e32 v140, v212, v140
	v_fmac_f32_e32 v140, v211, v94
	global_store_dword v130, v140, s[86:87] offset:-4096
	v_mul_f32_e32 v141, v212, v141
	v_fmac_f32_e32 v141, v211, v90
	global_store_dword v130, v141, s[86:87] offset:-4032
	v_mul_f32_e32 v142, v212, v142
	v_fmac_f32_e32 v142, v211, v86
	global_store_dword v130, v142, s[86:87] offset:-3968
	v_mul_f32_e32 v143, v212, v143
	v_fmac_f32_e32 v143, v211, v82
	global_store_dword v130, v143, s[86:87] offset:-3904
	v_mul_f32_e32 v144, v212, v144
	v_fmac_f32_e32 v144, v211, v95
	global_store_dword v130, v144, s[86:87]
	v_mul_f32_e32 v145, v212, v145
	v_fmac_f32_e32 v145, v211, v91
	global_store_dword v130, v145, s[86:87] offset:64
	v_mul_f32_e32 v146, v212, v146
	v_fmac_f32_e32 v146, v211, v87
	global_store_dword v130, v146, s[86:87] offset:128
	v_mul_f32_e32 v147, v212, v147
	v_fmac_f32_e32 v147, v211, v83
	global_store_dword v130, v147, s[86:87] offset:192
	v_mul_f32_e32 v148, v212, v148
	v_fmac_f32_e32 v148, v211, v96
	global_store_dword v131, v148, s[86:87] offset:-4096
	v_mul_f32_e32 v149, v212, v149
	v_fmac_f32_e32 v149, v211, v92
	global_store_dword v131, v149, s[86:87] offset:-4032
	v_mul_f32_e32 v150, v212, v150
	v_fmac_f32_e32 v150, v211, v88
	global_store_dword v131, v150, s[86:87] offset:-3968
	v_mul_f32_e32 v151, v212, v151
	v_fmac_f32_e32 v151, v211, v84
	global_store_dword v131, v151, s[86:87] offset:-3904
	v_mul_f32_e32 v152, v212, v152
	v_fmac_f32_e32 v152, v211, v97
	global_store_dword v131, v152, s[86:87]
	v_mul_f32_e32 v153, v212, v153
	v_fmac_f32_e32 v153, v211, v93
	global_store_dword v131, v153, s[86:87] offset:64
	v_mul_f32_e32 v154, v212, v154
	v_fmac_f32_e32 v154, v211, v89
	global_store_dword v131, v154, s[86:87] offset:128
	v_mul_f32_e32 v155, v212, v155
	v_fmac_f32_e32 v155, v211, v85
	global_store_dword v131, v155, s[86:87] offset:192
	v_add_u32_e32 v130, 0x40000, v138
	v_add_u32_e32 v131, 0x2000, v130
	global_load_dword v140, v130, s[86:87] offset:-4096
	global_load_dword v141, v130, s[86:87] offset:-4032
	global_load_dword v142, v130, s[86:87] offset:-3968
	global_load_dword v143, v130, s[86:87] offset:-3904
	global_load_dword v144, v130, s[86:87]
	global_load_dword v145, v130, s[86:87] offset:64
	global_load_dword v146, v130, s[86:87] offset:128
	global_load_dword v147, v130, s[86:87] offset:192
	global_load_dword v148, v131, s[86:87] offset:-4096
	global_load_dword v149, v131, s[86:87] offset:-4032
	global_load_dword v150, v131, s[86:87] offset:-3968
	global_load_dword v151, v131, s[86:87] offset:-3904
	global_load_dword v152, v131, s[86:87]
	global_load_dword v153, v131, s[86:87] offset:64
	global_load_dword v154, v131, s[86:87] offset:128
	global_load_dword v155, v131, s[86:87] offset:192
	s_waitcnt vmcnt(32)
;     ...
;     for (int ms = 0; ms < 8; ++ms) {
;       asm volatile("" ::: "memory");
; #pragma unroll
;       for (int ns = 0; ns < 4; ++ns)
; #pragma unroll
;         for (int j = 0; j < 4; ++j) {
;           int row = m0 + wm * 128 + ms * 16 + quad * 4 + j;
;           int col = n0 + wn * 64 + ns * 16 + l15;
;           const size_t xi = (size_t)row * D + col;
;           const float xv = xin ? xin[xi] : P.out[xi];
;           P.out[xi] = alpha * xv + sc * acc[ms][ns][j];
;         }
	v_mul_f32_e32 v156, v212, v156
	v_fmac_f32_e32 v156, v211, v78
	global_store_dword v132, v156, s[86:87] offset:-4096
	v_mul_f32_e32 v157, v212, v157
	v_fmac_f32_e32 v157, v211, v74
	global_store_dword v132, v157, s[86:87] offset:-4032
	v_mul_f32_e32 v158, v212, v158
	v_fmac_f32_e32 v158, v211, v70
	global_store_dword v132, v158, s[86:87] offset:-3968
	v_mul_f32_e32 v159, v212, v159
	v_fmac_f32_e32 v159, v211, v66
	global_store_dword v132, v159, s[86:87] offset:-3904
	v_mul_f32_e32 v160, v212, v160
	v_fmac_f32_e32 v160, v211, v79
	global_store_dword v132, v160, s[86:87]
	v_mul_f32_e32 v161, v212, v161
	v_fmac_f32_e32 v161, v211, v75
	global_store_dword v132, v161, s[86:87] offset:64
	v_mul_f32_e32 v162, v212, v162
	v_fmac_f32_e32 v162, v211, v71
	global_store_dword v132, v162, s[86:87] offset:128
	v_mul_f32_e32 v163, v212, v163
	v_fmac_f32_e32 v163, v211, v67
	global_store_dword v132, v163, s[86:87] offset:192
	v_mul_f32_e32 v164, v212, v164
	v_fmac_f32_e32 v164, v211, v80
	global_store_dword v133, v164, s[86:87] offset:-4096
	v_mul_f32_e32 v165, v212, v165
	v_fmac_f32_e32 v165, v211, v76
	global_store_dword v133, v165, s[86:87] offset:-4032
	v_mul_f32_e32 v166, v212, v166
	v_fmac_f32_e32 v166, v211, v72
	global_store_dword v133, v166, s[86:87] offset:-3968
	v_mul_f32_e32 v167, v212, v167
	v_fmac_f32_e32 v167, v211, v68
	global_store_dword v133, v167, s[86:87] offset:-3904
	v_mul_f32_e32 v168, v212, v168
	v_fmac_f32_e32 v168, v211, v81
	global_store_dword v133, v168, s[86:87]
	v_mul_f32_e32 v169, v212, v169
	v_fmac_f32_e32 v169, v211, v77
	global_store_dword v133, v169, s[86:87] offset:64
	v_mul_f32_e32 v170, v212, v170
	v_fmac_f32_e32 v170, v211, v73
	global_store_dword v133, v170, s[86:87] offset:128
	v_mul_f32_e32 v171, v212, v171
	v_fmac_f32_e32 v171, v211, v69
	global_store_dword v133, v171, s[86:87] offset:192
	v_add_u32_e32 v132, 0x50000, v138
	v_add_u32_e32 v133, 0x2000, v132
	global_load_dword v156, v132, s[86:87] offset:-4096
	global_load_dword v157, v132, s[86:87] offset:-4032
	global_load_dword v158, v132, s[86:87] offset:-3968
	global_load_dword v159, v132, s[86:87] offset:-3904
	global_load_dword v160, v132, s[86:87]
	global_load_dword v161, v132, s[86:87] offset:64
	global_load_dword v162, v132, s[86:87] offset:128
	global_load_dword v163, v132, s[86:87] offset:192
	global_load_dword v164, v133, s[86:87] offset:-4096
	global_load_dword v165, v133, s[86:87] offset:-4032
	global_load_dword v166, v133, s[86:87] offset:-3968
	global_load_dword v167, v133, s[86:87] offset:-3904
	global_load_dword v168, v133, s[86:87]
	global_load_dword v169, v133, s[86:87] offset:64
	global_load_dword v170, v133, s[86:87] offset:128
	global_load_dword v171, v133, s[86:87] offset:192
	s_waitcnt vmcnt(32)
	v_mul_f32_e32 v140, v212, v140
	v_fmac_f32_e32 v140, v211, v62
	global_store_dword v130, v140, s[86:87] offset:-4096
	v_mul_f32_e32 v141, v212, v141
	v_fmac_f32_e32 v141, v211, v58
	global_store_dword v130, v141, s[86:87] offset:-4032
	v_mul_f32_e32 v142, v212, v142
	v_fmac_f32_e32 v142, v211, v54
	global_store_dword v130, v142, s[86:87] offset:-3968
	v_mul_f32_e32 v143, v212, v143
	v_fmac_f32_e32 v143, v211, v50
	global_store_dword v130, v143, s[86:87] offset:-3904
	v_mul_f32_e32 v144, v212, v144
	v_fmac_f32_e32 v144, v211, v63
	global_store_dword v130, v144, s[86:87]
	v_mul_f32_e32 v145, v212, v145
	v_fmac_f32_e32 v145, v211, v59
	global_store_dword v130, v145, s[86:87] offset:64
	v_mul_f32_e32 v146, v212, v146
	v_fmac_f32_e32 v146, v211, v55
	global_store_dword v130, v146, s[86:87] offset:128
	v_mul_f32_e32 v147, v212, v147
	v_fmac_f32_e32 v147, v211, v51
	global_store_dword v130, v147, s[86:87] offset:192
	v_mul_f32_e32 v148, v212, v148
	v_fmac_f32_e32 v148, v211, v64
	global_store_dword v131, v148, s[86:87] offset:-4096
	v_mul_f32_e32 v149, v212, v149
	v_fmac_f32_e32 v149, v211, v60
	global_store_dword v131, v149, s[86:87] offset:-4032
	v_mul_f32_e32 v150, v212, v150
	v_fmac_f32_e32 v150, v211, v56
	global_store_dword v131, v150, s[86:87] offset:-3968
	v_mul_f32_e32 v151, v212, v151
	v_fmac_f32_e32 v151, v211, v52
	global_store_dword v131, v151, s[86:87] offset:-3904
	v_mul_f32_e32 v152, v212, v152
	v_fmac_f32_e32 v152, v211, v65
	global_store_dword v131, v152, s[86:87]
	v_mul_f32_e32 v153, v212, v153
	v_fmac_f32_e32 v153, v211, v61
	global_store_dword v131, v153, s[86:87] offset:64
	v_mul_f32_e32 v154, v212, v154
	v_fmac_f32_e32 v154, v211, v57
	global_store_dword v131, v154, s[86:87] offset:128
	v_mul_f32_e32 v155, v212, v155
	v_fmac_f32_e32 v155, v211, v53
	global_store_dword v131, v155, s[86:87] offset:192
	v_add_u32_e32 v130, 0x60000, v138
	v_add_u32_e32 v131, 0x2000, v130
	global_load_dword v140, v130, s[86:87] offset:-4096
	global_load_dword v141, v130, s[86:87] offset:-4032
	global_load_dword v142, v130, s[86:87] offset:-3968
	global_load_dword v143, v130, s[86:87] offset:-3904
	global_load_dword v144, v130, s[86:87]
	global_load_dword v145, v130, s[86:87] offset:64
	global_load_dword v146, v130, s[86:87] offset:128
	global_load_dword v147, v130, s[86:87] offset:192
	global_load_dword v148, v131, s[86:87] offset:-4096
	global_load_dword v149, v131, s[86:87] offset:-4032
	global_load_dword v150, v131, s[86:87] offset:-3968
	global_load_dword v151, v131, s[86:87] offset:-3904
	global_load_dword v152, v131, s[86:87]
	global_load_dword v153, v131, s[86:87] offset:64
	global_load_dword v154, v131, s[86:87] offset:128
	global_load_dword v155, v131, s[86:87] offset:192
	s_waitcnt vmcnt(32)
;     ...
;     for (int ms = 0; ms < 8; ++ms) {
;       asm volatile("" ::: "memory");
; #pragma unroll
;       for (int ns = 0; ns < 4; ++ns)
; #pragma unroll
;         for (int j = 0; j < 4; ++j) {
;           int row = m0 + wm * 128 + ms * 16 + quad * 4 + j;
;           int col = n0 + wn * 64 + ns * 16 + l15;
;           const size_t xi = (size_t)row * D + col;
;           const float xv = xin ? xin[xi] : P.out[xi];
;           P.out[xi] = alpha * xv + sc * acc[ms][ns][j];
;         }
	v_mul_f32_e32 v156, v212, v156
	v_fmac_f32_e32 v156, v211, v46
	global_store_dword v132, v156, s[86:87] offset:-4096
	v_mul_f32_e32 v157, v212, v157
	v_fmac_f32_e32 v157, v211, v42
	global_store_dword v132, v157, s[86:87] offset:-4032
	v_mul_f32_e32 v158, v212, v158
	v_fmac_f32_e32 v158, v211, v38
	global_store_dword v132, v158, s[86:87] offset:-3968
	v_mul_f32_e32 v159, v212, v159
	v_fmac_f32_e32 v159, v211, v34
	global_store_dword v132, v159, s[86:87] offset:-3904
	v_mul_f32_e32 v160, v212, v160
	v_fmac_f32_e32 v160, v211, v47
	global_store_dword v132, v160, s[86:87]
	v_mul_f32_e32 v161, v212, v161
	v_fmac_f32_e32 v161, v211, v43
	global_store_dword v132, v161, s[86:87] offset:64
	v_mul_f32_e32 v162, v212, v162
	v_fmac_f32_e32 v162, v211, v39
	global_store_dword v132, v162, s[86:87] offset:128
	v_mul_f32_e32 v163, v212, v163
	v_fmac_f32_e32 v163, v211, v35
	global_store_dword v132, v163, s[86:87] offset:192
	v_mul_f32_e32 v164, v212, v164
	v_fmac_f32_e32 v164, v211, v48
	global_store_dword v133, v164, s[86:87] offset:-4096
	v_mul_f32_e32 v165, v212, v165
	v_fmac_f32_e32 v165, v211, v44
	global_store_dword v133, v165, s[86:87] offset:-4032
	v_mul_f32_e32 v166, v212, v166
	v_fmac_f32_e32 v166, v211, v40
	global_store_dword v133, v166, s[86:87] offset:-3968
	v_mul_f32_e32 v167, v212, v167
	v_fmac_f32_e32 v167, v211, v36
	global_store_dword v133, v167, s[86:87] offset:-3904
	v_mul_f32_e32 v168, v212, v168
	v_fmac_f32_e32 v168, v211, v49
	global_store_dword v133, v168, s[86:87]
	v_mul_f32_e32 v169, v212, v169
	v_fmac_f32_e32 v169, v211, v45
	global_store_dword v133, v169, s[86:87] offset:64
	v_mul_f32_e32 v170, v212, v170
	v_fmac_f32_e32 v170, v211, v41
	global_store_dword v133, v170, s[86:87] offset:128
	v_mul_f32_e32 v171, v212, v171
	v_fmac_f32_e32 v171, v211, v37
	global_store_dword v133, v171, s[86:87] offset:192
	v_add_u32_e32 v132, 0x70000, v138
	v_add_u32_e32 v133, 0x2000, v132
	global_load_dword v156, v132, s[86:87] offset:-4096
	global_load_dword v157, v132, s[86:87] offset:-4032
	global_load_dword v158, v132, s[86:87] offset:-3968
	global_load_dword v159, v132, s[86:87] offset:-3904
	global_load_dword v160, v132, s[86:87]
	global_load_dword v161, v132, s[86:87] offset:64
	global_load_dword v162, v132, s[86:87] offset:128
	global_load_dword v163, v132, s[86:87] offset:192
	global_load_dword v164, v133, s[86:87] offset:-4096
	global_load_dword v165, v133, s[86:87] offset:-4032
	global_load_dword v166, v133, s[86:87] offset:-3968
	global_load_dword v167, v133, s[86:87] offset:-3904
	global_load_dword v168, v133, s[86:87]
	global_load_dword v169, v133, s[86:87] offset:64
	global_load_dword v170, v133, s[86:87] offset:128
	global_load_dword v171, v133, s[86:87] offset:192
	s_waitcnt vmcnt(32)
	v_mul_f32_e32 v140, v212, v140
	v_fmac_f32_e32 v140, v211, v30
	global_store_dword v130, v140, s[86:87] offset:-4096
	v_mul_f32_e32 v141, v212, v141
	v_fmac_f32_e32 v141, v211, v26
	global_store_dword v130, v141, s[86:87] offset:-4032
	v_mul_f32_e32 v142, v212, v142
	v_fmac_f32_e32 v142, v211, v22
	global_store_dword v130, v142, s[86:87] offset:-3968
	v_mul_f32_e32 v143, v212, v143
	v_fmac_f32_e32 v143, v211, v18
	global_store_dword v130, v143, s[86:87] offset:-3904
	v_mul_f32_e32 v144, v212, v144
	v_fmac_f32_e32 v144, v211, v31
	global_store_dword v130, v144, s[86:87]
	v_mul_f32_e32 v145, v212, v145
	v_fmac_f32_e32 v145, v211, v27
	global_store_dword v130, v145, s[86:87] offset:64
	v_mul_f32_e32 v146, v212, v146
	v_fmac_f32_e32 v146, v211, v23
	global_store_dword v130, v146, s[86:87] offset:128
	v_mul_f32_e32 v147, v212, v147
	v_fmac_f32_e32 v147, v211, v19
	global_store_dword v130, v147, s[86:87] offset:192
	v_mul_f32_e32 v148, v212, v148
	v_fmac_f32_e32 v148, v211, v32
	global_store_dword v131, v148, s[86:87] offset:-4096
	v_mul_f32_e32 v149, v212, v149
	v_fmac_f32_e32 v149, v211, v28
	global_store_dword v131, v149, s[86:87] offset:-4032
	v_mul_f32_e32 v150, v212, v150
	v_fmac_f32_e32 v150, v211, v24
	global_store_dword v131, v150, s[86:87] offset:-3968
	v_mul_f32_e32 v151, v212, v151
	v_fmac_f32_e32 v151, v211, v20
	global_store_dword v131, v151, s[86:87] offset:-3904
	v_mul_f32_e32 v152, v212, v152
	v_fmac_f32_e32 v152, v211, v33
	global_store_dword v131, v152, s[86:87]
	v_mul_f32_e32 v153, v212, v153
	v_fmac_f32_e32 v153, v211, v29
	global_store_dword v131, v153, s[86:87] offset:64
	v_mul_f32_e32 v154, v212, v154
	v_fmac_f32_e32 v154, v211, v25
	global_store_dword v131, v154, s[86:87] offset:128
	v_mul_f32_e32 v155, v212, v155
	v_fmac_f32_e32 v155, v211, v21
	global_store_dword v131, v155, s[86:87] offset:192
	s_waitcnt vmcnt(16)
	v_mul_f32_e32 v156, v212, v156
	v_fmac_f32_e32 v156, v211, v14
	global_store_dword v132, v156, s[86:87] offset:-4096
	v_mul_f32_e32 v157, v212, v157
	v_fmac_f32_e32 v157, v211, v10
	global_store_dword v132, v157, s[86:87] offset:-4032
	v_mul_f32_e32 v158, v212, v158
	v_fmac_f32_e32 v158, v211, v6
	global_store_dword v132, v158, s[86:87] offset:-3968
	v_mul_f32_e32 v159, v212, v159
	v_fmac_f32_e32 v159, v211, v2
	global_store_dword v132, v159, s[86:87] offset:-3904
	v_mul_f32_e32 v160, v212, v160
	v_fmac_f32_e32 v160, v211, v15
	global_store_dword v132, v160, s[86:87]
	v_mul_f32_e32 v161, v212, v161
	v_fmac_f32_e32 v161, v211, v11
	global_store_dword v132, v161, s[86:87] offset:64
	v_mul_f32_e32 v162, v212, v162
	v_fmac_f32_e32 v162, v211, v7
	global_store_dword v132, v162, s[86:87] offset:128
	v_mul_f32_e32 v163, v212, v163
	v_fmac_f32_e32 v163, v211, v3
	global_store_dword v132, v163, s[86:87] offset:192
	v_mul_f32_e32 v164, v212, v164
	v_fmac_f32_e32 v164, v211, v16
	global_store_dword v133, v164, s[86:87] offset:-4096
	v_mul_f32_e32 v165, v212, v165
	v_fmac_f32_e32 v165, v211, v12
	global_store_dword v133, v165, s[86:87] offset:-4032
	v_mul_f32_e32 v166, v212, v166
	v_fmac_f32_e32 v166, v211, v8
	global_store_dword v133, v166, s[86:87] offset:-3968
	v_mul_f32_e32 v167, v212, v167
	v_fmac_f32_e32 v167, v211, v4
	global_store_dword v133, v167, s[86:87] offset:-3904
	v_mul_f32_e32 v168, v212, v168
	v_fmac_f32_e32 v168, v211, v17
	global_store_dword v133, v168, s[86:87]
	v_mul_f32_e32 v169, v212, v169
	v_fmac_f32_e32 v169, v211, v13
	global_store_dword v133, v169, s[86:87] offset:64
	v_mul_f32_e32 v170, v212, v170
	v_fmac_f32_e32 v170, v211, v9
	global_store_dword v133, v170, s[86:87] offset:128
	v_mul_f32_e32 v171, v212, v171
	v_fmac_f32_e32 v171, v211, v5
	global_store_dword v133, v171, s[86:87] offset:192
	s_cbranch_vccnz .LBB0_159

;     ...
;     for (int ms = 0; ms < 8; ++ms) {
;       asm volatile("" ::: "memory");
; #pragma unroll
;       for (int ns = 0; ns < 4; ++ns)
; #pragma unroll
;         for (int j = 0; j < 4; ++j) {
;           int row = m0 + wm * 128 + ms * 16 + quad * 4 + j;
;           int col = n0 + wn * 64 + ns * 16 + l15;
;           const size_t xi = (size_t)row * D + col;
;           const float xv = xin ? xin[xi] : P.out[xi];
;           P.out[xi] = alpha * xv + sc * acc[ms][ns][j];
;         }
.LBB0_289:
	v_add_u32_e32 v136, s8, v207
	v_or_b32_e32 v130, s12, v208
	v_lshlrev_b32_e32 v136, 12, v136
	v_lshl_add_u32 v138, v130, 2, v136
	v_add_u32_e32 v138, 0x1000, v138
	s_and_b64 vcc, exec, s[10:11]
	v_mov_b32_e32 v130, v138
	v_add_u32_e32 v131, 0x2000, v130
	global_load_dword v140, v130, s[86:87] offset:-4096
	global_load_dword v141, v130, s[86:87] offset:-4032
	global_load_dword v142, v130, s[86:87] offset:-3968
	global_load_dword v143, v130, s[86:87] offset:-3904
	global_load_dword v144, v130, s[86:87]
	global_load_dword v145, v130, s[86:87] offset:64
	global_load_dword v146, v130, s[86:87] offset:128
	global_load_dword v147, v130, s[86:87] offset:192
	global_load_dword v148, v131, s[86:87] offset:-4096
	global_load_dword v149, v131, s[86:87] offset:-4032
	global_load_dword v150, v131, s[86:87] offset:-3968
	global_load_dword v151, v131, s[86:87] offset:-3904
	global_load_dword v152, v131, s[86:87]
	global_load_dword v153, v131, s[86:87] offset:64
	global_load_dword v154, v131, s[86:87] offset:128
	global_load_dword v155, v131, s[86:87] offset:192
	v_add_u32_e32 v132, 0x10000, v138
	v_add_u32_e32 v133, 0x2000, v132
	global_load_dword v156, v132, s[86:87] offset:-4096
	global_load_dword v157, v132, s[86:87] offset:-4032
	global_load_dword v158, v132, s[86:87] offset:-3968
	global_load_dword v159, v132, s[86:87] offset:-3904
	global_load_dword v160, v132, s[86:87]
	global_load_dword v161, v132, s[86:87] offset:64
	global_load_dword v162, v132, s[86:87] offset:128
	global_load_dword v163, v132, s[86:87] offset:192
	global_load_dword v164, v133, s[86:87] offset:-4096
	global_load_dword v165, v133, s[86:87] offset:-4032
	global_load_dword v166, v133, s[86:87] offset:-3968
	global_load_dword v167, v133, s[86:87] offset:-3904
	global_load_dword v168, v133, s[86:87]
	global_load_dword v169, v133, s[86:87] offset:64
	global_load_dword v170, v133, s[86:87] offset:128
	global_load_dword v171, v133, s[86:87] offset:192
	s_waitcnt vmcnt(16)
	v_mul_f32_e32 v140, v212, v140
	v_fmac_f32_e32 v140, v181, v126
	global_store_dword v130, v140, s[86:87] offset:-4096
	v_mul_f32_e32 v141, v212, v141
	v_fmac_f32_e32 v141, v181, v122
	global_store_dword v130, v141, s[86:87] offset:-4032
	v_mul_f32_e32 v142, v212, v142
	v_fmac_f32_e32 v142, v181, v118
	global_store_dword v130, v142, s[86:87] offset:-3968
	v_mul_f32_e32 v143, v212, v143
	v_fmac_f32_e32 v143, v181, v114
	global_store_dword v130, v143, s[86:87] offset:-3904
	v_mul_f32_e32 v144, v212, v144
	v_fmac_f32_e32 v144, v181, v127
	global_store_dword v130, v144, s[86:87]
	v_mul_f32_e32 v145, v212, v145
	v_fmac_f32_e32 v145, v181, v123
	global_store_dword v130, v145, s[86:87] offset:64
	v_mul_f32_e32 v146, v212, v146
	v_fmac_f32_e32 v146, v181, v119
	global_store_dword v130, v146, s[86:87] offset:128
	v_mul_f32_e32 v147, v212, v147
	v_fmac_f32_e32 v147, v181, v115
	global_store_dword v130, v147, s[86:87] offset:192
	v_mul_f32_e32 v148, v212, v148
	v_fmac_f32_e32 v148, v181, v128
	global_store_dword v131, v148, s[86:87] offset:-4096
	v_mul_f32_e32 v149, v212, v149
	v_fmac_f32_e32 v149, v181, v124
	global_store_dword v131, v149, s[86:87] offset:-4032
	v_mul_f32_e32 v150, v212, v150
	v_fmac_f32_e32 v150, v181, v120
	global_store_dword v131, v150, s[86:87] offset:-3968
	v_mul_f32_e32 v151, v212, v151
	v_fmac_f32_e32 v151, v181, v116
	global_store_dword v131, v151, s[86:87] offset:-3904
	v_mul_f32_e32 v152, v212, v152
	v_fmac_f32_e32 v152, v181, v129
	global_store_dword v131, v152, s[86:87]
	v_mul_f32_e32 v153, v212, v153
	v_fmac_f32_e32 v153, v181, v125
	global_store_dword v131, v153, s[86:87] offset:64
	v_mul_f32_e32 v154, v212, v154
	v_fmac_f32_e32 v154, v181, v121
	global_store_dword v131, v154, s[86:87] offset:128
	v_mul_f32_e32 v155, v212, v155
	v_fmac_f32_e32 v155, v181, v117
	global_store_dword v131, v155, s[86:87] offset:192
	v_add_u32_e32 v130, 0x20000, v138
	v_add_u32_e32 v131, 0x2000, v130
	global_load_dword v140, v130, s[86:87] offset:-4096
	global_load_dword v141, v130, s[86:87] offset:-4032
	global_load_dword v142, v130, s[86:87] offset:-3968
	global_load_dword v143, v130, s[86:87] offset:-3904
	global_load_dword v144, v130, s[86:87]
	global_load_dword v145, v130, s[86:87] offset:64
	global_load_dword v146, v130, s[86:87] offset:128
	global_load_dword v147, v130, s[86:87] offset:192
	global_load_dword v148, v131, s[86:87] offset:-4096
	global_load_dword v149, v131, s[86:87] offset:-4032
	global_load_dword v150, v131, s[86:87] offset:-3968
	global_load_dword v151, v131, s[86:87] offset:-3904
	global_load_dword v152, v131, s[86:87]
	global_load_dword v153, v131, s[86:87] offset:64
	global_load_dword v154, v131, s[86:87] offset:128
	global_load_dword v155, v131, s[86:87] offset:192
	s_waitcnt vmcnt(32)
;     ...
;     for (int ms = 0; ms < 8; ++ms) {
;       asm volatile("" ::: "memory");
; #pragma unroll
;       for (int ns = 0; ns < 4; ++ns)
; #pragma unroll
;         for (int j = 0; j < 4; ++j) {
;           int row = m0 + wm * 128 + ms * 16 + quad * 4 + j;
;           int col = n0 + wn * 64 + ns * 16 + l15;
;           const size_t xi = (size_t)row * D + col;
;           const float xv = xin ? xin[xi] : P.out[xi];
;           P.out[xi] = alpha * xv + sc * acc[ms][ns][j];
;         }
	v_mul_f32_e32 v156, v212, v156
	v_fmac_f32_e32 v156, v181, v110
	global_store_dword v132, v156, s[86:87] offset:-4096
	v_mul_f32_e32 v157, v212, v157
	v_fmac_f32_e32 v157, v181, v106
	global_store_dword v132, v157, s[86:87] offset:-4032
	v_mul_f32_e32 v158, v212, v158
	v_fmac_f32_e32 v158, v181, v102
	global_store_dword v132, v158, s[86:87] offset:-3968
	v_mul_f32_e32 v159, v212, v159
	v_fmac_f32_e32 v159, v181, v98
	global_store_dword v132, v159, s[86:87] offset:-3904
	v_mul_f32_e32 v160, v212, v160
	v_fmac_f32_e32 v160, v181, v111
	global_store_dword v132, v160, s[86:87]
	v_mul_f32_e32 v161, v212, v161
	v_fmac_f32_e32 v161, v181, v107
	global_store_dword v132, v161, s[86:87] offset:64
	v_mul_f32_e32 v162, v212, v162
	v_fmac_f32_e32 v162, v181, v103
	global_store_dword v132, v162, s[86:87] offset:128
	v_mul_f32_e32 v163, v212, v163
	v_fmac_f32_e32 v163, v181, v99
	global_store_dword v132, v163, s[86:87] offset:192
	v_mul_f32_e32 v164, v212, v164
	v_fmac_f32_e32 v164, v181, v112
	global_store_dword v133, v164, s[86:87] offset:-4096
	v_mul_f32_e32 v165, v212, v165
	v_fmac_f32_e32 v165, v181, v108
	global_store_dword v133, v165, s[86:87] offset:-4032
	v_mul_f32_e32 v166, v212, v166
	v_fmac_f32_e32 v166, v181, v104
	global_store_dword v133, v166, s[86:87] offset:-3968
	v_mul_f32_e32 v167, v212, v167
	v_fmac_f32_e32 v167, v181, v100
	global_store_dword v133, v167, s[86:87] offset:-3904
	v_mul_f32_e32 v168, v212, v168
	v_fmac_f32_e32 v168, v181, v113
	global_store_dword v133, v168, s[86:87]
	v_mul_f32_e32 v169, v212, v169
	v_fmac_f32_e32 v169, v181, v109
	global_store_dword v133, v169, s[86:87] offset:64
	v_mul_f32_e32 v170, v212, v170
	v_fmac_f32_e32 v170, v181, v105
	global_store_dword v133, v170, s[86:87] offset:128
	v_mul_f32_e32 v171, v212, v171
	v_fmac_f32_e32 v171, v181, v101
	global_store_dword v133, v171, s[86:87] offset:192
	v_add_u32_e32 v132, 0x30000, v138
	v_add_u32_e32 v133, 0x2000, v132
	global_load_dword v156, v132, s[86:87] offset:-4096
	global_load_dword v157, v132, s[86:87] offset:-4032
	global_load_dword v158, v132, s[86:87] offset:-3968
	global_load_dword v159, v132, s[86:87] offset:-3904
	global_load_dword v160, v132, s[86:87]
	global_load_dword v161, v132, s[86:87] offset:64
	global_load_dword v162, v132, s[86:87] offset:128
	global_load_dword v163, v132, s[86:87] offset:192
	global_load_dword v164, v133, s[86:87] offset:-4096
	global_load_dword v165, v133, s[86:87] offset:-4032
	global_load_dword v166, v133, s[86:87] offset:-3968
	global_load_dword v167, v133, s[86:87] offset:-3904
	global_load_dword v168, v133, s[86:87]
	global_load_dword v169, v133, s[86:87] offset:64
	global_load_dword v170, v133, s[86:87] offset:128
	global_load_dword v171, v133, s[86:87] offset:192
	s_waitcnt vmcnt(32)
	v_mul_f32_e32 v140, v212, v140
	v_fmac_f32_e32 v140, v181, v94
	global_store_dword v130, v140, s[86:87] offset:-4096
	v_mul_f32_e32 v141, v212, v141
	v_fmac_f32_e32 v141, v181, v90
	global_store_dword v130, v141, s[86:87] offset:-4032
	v_mul_f32_e32 v142, v212, v142
	v_fmac_f32_e32 v142, v181, v86
	global_store_dword v130, v142, s[86:87] offset:-3968
	v_mul_f32_e32 v143, v212, v143
	v_fmac_f32_e32 v143, v181, v82
	global_store_dword v130, v143, s[86:87] offset:-3904
	v_mul_f32_e32 v144, v212, v144
	v_fmac_f32_e32 v144, v181, v95
	global_store_dword v130, v144, s[86:87]
	v_mul_f32_e32 v145, v212, v145
	v_fmac_f32_e32 v145, v181, v91
	global_store_dword v130, v145, s[86:87] offset:64
	v_mul_f32_e32 v146, v212, v146
	v_fmac_f32_e32 v146, v181, v87
	global_store_dword v130, v146, s[86:87] offset:128
	v_mul_f32_e32 v147, v212, v147
	v_fmac_f32_e32 v147, v181, v83
	global_store_dword v130, v147, s[86:87] offset:192
	v_mul_f32_e32 v148, v212, v148
	v_fmac_f32_e32 v148, v181, v96
	global_store_dword v131, v148, s[86:87] offset:-4096
	v_mul_f32_e32 v149, v212, v149
	v_fmac_f32_e32 v149, v181, v92
	global_store_dword v131, v149, s[86:87] offset:-4032
	v_mul_f32_e32 v150, v212, v150
	v_fmac_f32_e32 v150, v181, v88
	global_store_dword v131, v150, s[86:87] offset:-3968
	v_mul_f32_e32 v151, v212, v151
	v_fmac_f32_e32 v151, v181, v84
	global_store_dword v131, v151, s[86:87] offset:-3904
	v_mul_f32_e32 v152, v212, v152
	v_fmac_f32_e32 v152, v181, v97
	global_store_dword v131, v152, s[86:87]
	v_mul_f32_e32 v153, v212, v153
	v_fmac_f32_e32 v153, v181, v93
	global_store_dword v131, v153, s[86:87] offset:64
	v_mul_f32_e32 v154, v212, v154
	v_fmac_f32_e32 v154, v181, v89
	global_store_dword v131, v154, s[86:87] offset:128
	v_mul_f32_e32 v155, v212, v155
	v_fmac_f32_e32 v155, v181, v85
	global_store_dword v131, v155, s[86:87] offset:192
	v_add_u32_e32 v130, 0x40000, v138
	v_add_u32_e32 v131, 0x2000, v130
	global_load_dword v140, v130, s[86:87] offset:-4096
	global_load_dword v141, v130, s[86:87] offset:-4032
	global_load_dword v142, v130, s[86:87] offset:-3968
	global_load_dword v143, v130, s[86:87] offset:-3904
	global_load_dword v144, v130, s[86:87]
	global_load_dword v145, v130, s[86:87] offset:64
	global_load_dword v146, v130, s[86:87] offset:128
	global_load_dword v147, v130, s[86:87] offset:192
	global_load_dword v148, v131, s[86:87] offset:-4096
	global_load_dword v149, v131, s[86:87] offset:-4032
	global_load_dword v150, v131, s[86:87] offset:-3968
	global_load_dword v151, v131, s[86:87] offset:-3904
	global_load_dword v152, v131, s[86:87]
	global_load_dword v153, v131, s[86:87] offset:64
	global_load_dword v154, v131, s[86:87] offset:128
	global_load_dword v155, v131, s[86:87] offset:192
	s_waitcnt vmcnt(32)
;     ...
;     for (int ms = 0; ms < 8; ++ms) {
;       asm volatile("" ::: "memory");
; #pragma unroll
;       for (int ns = 0; ns < 4; ++ns)
; #pragma unroll
;         for (int j = 0; j < 4; ++j) {
;           int row = m0 + wm * 128 + ms * 16 + quad * 4 + j;
;           int col = n0 + wn * 64 + ns * 16 + l15;
;           const size_t xi = (size_t)row * D + col;
;           const float xv = xin ? xin[xi] : P.out[xi];
;           P.out[xi] = alpha * xv + sc * acc[ms][ns][j];
;         }
	v_mul_f32_e32 v156, v212, v156
	v_fmac_f32_e32 v156, v181, v78
	global_store_dword v132, v156, s[86:87] offset:-4096
	v_mul_f32_e32 v157, v212, v157
	v_fmac_f32_e32 v157, v181, v74
	global_store_dword v132, v157, s[86:87] offset:-4032
	v_mul_f32_e32 v158, v212, v158
	v_fmac_f32_e32 v158, v181, v70
	global_store_dword v132, v158, s[86:87] offset:-3968
	v_mul_f32_e32 v159, v212, v159
	v_fmac_f32_e32 v159, v181, v66
	global_store_dword v132, v159, s[86:87] offset:-3904
	v_mul_f32_e32 v160, v212, v160
	v_fmac_f32_e32 v160, v181, v79
	global_store_dword v132, v160, s[86:87]
	v_mul_f32_e32 v161, v212, v161
	v_fmac_f32_e32 v161, v181, v75
	global_store_dword v132, v161, s[86:87] offset:64
	v_mul_f32_e32 v162, v212, v162
	v_fmac_f32_e32 v162, v181, v71
	global_store_dword v132, v162, s[86:87] offset:128
	v_mul_f32_e32 v163, v212, v163
	v_fmac_f32_e32 v163, v181, v67
	global_store_dword v132, v163, s[86:87] offset:192
	v_mul_f32_e32 v164, v212, v164
	v_fmac_f32_e32 v164, v181, v80
	global_store_dword v133, v164, s[86:87] offset:-4096
	v_mul_f32_e32 v165, v212, v165
	v_fmac_f32_e32 v165, v181, v76
	global_store_dword v133, v165, s[86:87] offset:-4032
	v_mul_f32_e32 v166, v212, v166
	v_fmac_f32_e32 v166, v181, v72
	global_store_dword v133, v166, s[86:87] offset:-3968
	v_mul_f32_e32 v167, v212, v167
	v_fmac_f32_e32 v167, v181, v68
	global_store_dword v133, v167, s[86:87] offset:-3904
	v_mul_f32_e32 v168, v212, v168
	v_fmac_f32_e32 v168, v181, v81
	global_store_dword v133, v168, s[86:87]
	v_mul_f32_e32 v169, v212, v169
	v_fmac_f32_e32 v169, v181, v77
	global_store_dword v133, v169, s[86:87] offset:64
	v_mul_f32_e32 v170, v212, v170
	v_fmac_f32_e32 v170, v181, v73
	global_store_dword v133, v170, s[86:87] offset:128
	v_mul_f32_e32 v171, v212, v171
	v_fmac_f32_e32 v171, v181, v69
	global_store_dword v133, v171, s[86:87] offset:192
	v_add_u32_e32 v132, 0x50000, v138
	v_add_u32_e32 v133, 0x2000, v132
	global_load_dword v156, v132, s[86:87] offset:-4096
	global_load_dword v157, v132, s[86:87] offset:-4032
	global_load_dword v158, v132, s[86:87] offset:-3968
	global_load_dword v159, v132, s[86:87] offset:-3904
	global_load_dword v160, v132, s[86:87]
	global_load_dword v161, v132, s[86:87] offset:64
	global_load_dword v162, v132, s[86:87] offset:128
	global_load_dword v163, v132, s[86:87] offset:192
	global_load_dword v164, v133, s[86:87] offset:-4096
	global_load_dword v165, v133, s[86:87] offset:-4032
	global_load_dword v166, v133, s[86:87] offset:-3968
	global_load_dword v167, v133, s[86:87] offset:-3904
	global_load_dword v168, v133, s[86:87]
	global_load_dword v169, v133, s[86:87] offset:64
	global_load_dword v170, v133, s[86:87] offset:128
	global_load_dword v171, v133, s[86:87] offset:192
	s_waitcnt vmcnt(32)
	v_mul_f32_e32 v140, v212, v140
	v_fmac_f32_e32 v140, v181, v62
	global_store_dword v130, v140, s[86:87] offset:-4096
	v_mul_f32_e32 v141, v212, v141
	v_fmac_f32_e32 v141, v181, v58
	global_store_dword v130, v141, s[86:87] offset:-4032
	v_mul_f32_e32 v142, v212, v142
	v_fmac_f32_e32 v142, v181, v54
	global_store_dword v130, v142, s[86:87] offset:-3968
	v_mul_f32_e32 v143, v212, v143
	v_fmac_f32_e32 v143, v181, v50
	global_store_dword v130, v143, s[86:87] offset:-3904
	v_mul_f32_e32 v144, v212, v144
	v_fmac_f32_e32 v144, v181, v63
	global_store_dword v130, v144, s[86:87]
	v_mul_f32_e32 v145, v212, v145
	v_fmac_f32_e32 v145, v181, v59
	global_store_dword v130, v145, s[86:87] offset:64
	v_mul_f32_e32 v146, v212, v146
	v_fmac_f32_e32 v146, v181, v55
	global_store_dword v130, v146, s[86:87] offset:128
	v_mul_f32_e32 v147, v212, v147
	v_fmac_f32_e32 v147, v181, v51
	global_store_dword v130, v147, s[86:87] offset:192
	v_mul_f32_e32 v148, v212, v148
	v_fmac_f32_e32 v148, v181, v64
	global_store_dword v131, v148, s[86:87] offset:-4096
	v_mul_f32_e32 v149, v212, v149
	v_fmac_f32_e32 v149, v181, v60
	global_store_dword v131, v149, s[86:87] offset:-4032
	v_mul_f32_e32 v150, v212, v150
	v_fmac_f32_e32 v150, v181, v56
	global_store_dword v131, v150, s[86:87] offset:-3968
	v_mul_f32_e32 v151, v212, v151
	v_fmac_f32_e32 v151, v181, v52
	global_store_dword v131, v151, s[86:87] offset:-3904
	v_mul_f32_e32 v152, v212, v152
	v_fmac_f32_e32 v152, v181, v65
	global_store_dword v131, v152, s[86:87]
	v_mul_f32_e32 v153, v212, v153
	v_fmac_f32_e32 v153, v181, v61
	global_store_dword v131, v153, s[86:87] offset:64
	v_mul_f32_e32 v154, v212, v154
	v_fmac_f32_e32 v154, v181, v57
	global_store_dword v131, v154, s[86:87] offset:128
	v_mul_f32_e32 v155, v212, v155
	v_fmac_f32_e32 v155, v181, v53
	global_store_dword v131, v155, s[86:87] offset:192
	v_add_u32_e32 v130, 0x60000, v138
	v_add_u32_e32 v131, 0x2000, v130
	global_load_dword v140, v130, s[86:87] offset:-4096
	global_load_dword v141, v130, s[86:87] offset:-4032
	global_load_dword v142, v130, s[86:87] offset:-3968
	global_load_dword v143, v130, s[86:87] offset:-3904
	global_load_dword v144, v130, s[86:87]
	global_load_dword v145, v130, s[86:87] offset:64
	global_load_dword v146, v130, s[86:87] offset:128
	global_load_dword v147, v130, s[86:87] offset:192
	global_load_dword v148, v131, s[86:87] offset:-4096
	global_load_dword v149, v131, s[86:87] offset:-4032
	global_load_dword v150, v131, s[86:87] offset:-3968
	global_load_dword v151, v131, s[86:87] offset:-3904
	global_load_dword v152, v131, s[86:87]
	global_load_dword v153, v131, s[86:87] offset:64
	global_load_dword v154, v131, s[86:87] offset:128
	global_load_dword v155, v131, s[86:87] offset:192
	s_waitcnt vmcnt(32)
;     ...
;     for (int ms = 0; ms < 8; ++ms) {
;       asm volatile("" ::: "memory");
; #pragma unroll
;       for (int ns = 0; ns < 4; ++ns)
; #pragma unroll
;         for (int j = 0; j < 4; ++j) {
;           int row = m0 + wm * 128 + ms * 16 + quad * 4 + j;
;           int col = n0 + wn * 64 + ns * 16 + l15;
;           const size_t xi = (size_t)row * D + col;
;           const float xv = xin ? xin[xi] : P.out[xi];
;           P.out[xi] = alpha * xv + sc * acc[ms][ns][j];
;         }
	v_mul_f32_e32 v156, v212, v156
	v_fmac_f32_e32 v156, v181, v46
	global_store_dword v132, v156, s[86:87] offset:-4096
	v_mul_f32_e32 v157, v212, v157
	v_fmac_f32_e32 v157, v181, v42
	global_store_dword v132, v157, s[86:87] offset:-4032
	v_mul_f32_e32 v158, v212, v158
	v_fmac_f32_e32 v158, v181, v38
	global_store_dword v132, v158, s[86:87] offset:-3968
	v_mul_f32_e32 v159, v212, v159
	v_fmac_f32_e32 v159, v181, v34
	global_store_dword v132, v159, s[86:87] offset:-3904
	v_mul_f32_e32 v160, v212, v160
	v_fmac_f32_e32 v160, v181, v47
	global_store_dword v132, v160, s[86:87]
	v_mul_f32_e32 v161, v212, v161
	v_fmac_f32_e32 v161, v181, v43
	global_store_dword v132, v161, s[86:87] offset:64
	v_mul_f32_e32 v162, v212, v162
	v_fmac_f32_e32 v162, v181, v39
	global_store_dword v132, v162, s[86:87] offset:128
	v_mul_f32_e32 v163, v212, v163
	v_fmac_f32_e32 v163, v181, v35
	global_store_dword v132, v163, s[86:87] offset:192
	v_mul_f32_e32 v164, v212, v164
	v_fmac_f32_e32 v164, v181, v48
	global_store_dword v133, v164, s[86:87] offset:-4096
	v_mul_f32_e32 v165, v212, v165
	v_fmac_f32_e32 v165, v181, v44
	global_store_dword v133, v165, s[86:87] offset:-4032
	v_mul_f32_e32 v166, v212, v166
	v_fmac_f32_e32 v166, v181, v40
	global_store_dword v133, v166, s[86:87] offset:-3968
	v_mul_f32_e32 v167, v212, v167
	v_fmac_f32_e32 v167, v181, v36
	global_store_dword v133, v167, s[86:87] offset:-3904
	v_mul_f32_e32 v168, v212, v168
	v_fmac_f32_e32 v168, v181, v49
	global_store_dword v133, v168, s[86:87]
	v_mul_f32_e32 v169, v212, v169
	v_fmac_f32_e32 v169, v181, v45
	global_store_dword v133, v169, s[86:87] offset:64
	v_mul_f32_e32 v170, v212, v170
	v_fmac_f32_e32 v170, v181, v41
	global_store_dword v133, v170, s[86:87] offset:128
	v_mul_f32_e32 v171, v212, v171
	v_fmac_f32_e32 v171, v181, v37
	global_store_dword v133, v171, s[86:87] offset:192
	v_add_u32_e32 v132, 0x70000, v138
	v_add_u32_e32 v133, 0x2000, v132
	global_load_dword v156, v132, s[86:87] offset:-4096
	global_load_dword v157, v132, s[86:87] offset:-4032
	global_load_dword v158, v132, s[86:87] offset:-3968
	global_load_dword v159, v132, s[86:87] offset:-3904
	global_load_dword v160, v132, s[86:87]
	global_load_dword v161, v132, s[86:87] offset:64
	global_load_dword v162, v132, s[86:87] offset:128
	global_load_dword v163, v132, s[86:87] offset:192
	global_load_dword v164, v133, s[86:87] offset:-4096
	global_load_dword v165, v133, s[86:87] offset:-4032
	global_load_dword v166, v133, s[86:87] offset:-3968
	global_load_dword v167, v133, s[86:87] offset:-3904
	global_load_dword v168, v133, s[86:87]
	global_load_dword v169, v133, s[86:87] offset:64
	global_load_dword v170, v133, s[86:87] offset:128
	global_load_dword v171, v133, s[86:87] offset:192
	s_waitcnt vmcnt(32)
	v_mul_f32_e32 v140, v212, v140
	v_fmac_f32_e32 v140, v181, v30
	global_store_dword v130, v140, s[86:87] offset:-4096
	v_mul_f32_e32 v141, v212, v141
	v_fmac_f32_e32 v141, v181, v26
	global_store_dword v130, v141, s[86:87] offset:-4032
	v_mul_f32_e32 v142, v212, v142
	v_fmac_f32_e32 v142, v181, v22
	global_store_dword v130, v142, s[86:87] offset:-3968
	v_mul_f32_e32 v143, v212, v143
	v_fmac_f32_e32 v143, v181, v18
	global_store_dword v130, v143, s[86:87] offset:-3904
	v_mul_f32_e32 v144, v212, v144
	v_fmac_f32_e32 v144, v181, v31
	global_store_dword v130, v144, s[86:87]
	v_mul_f32_e32 v145, v212, v145
	v_fmac_f32_e32 v145, v181, v27
	global_store_dword v130, v145, s[86:87] offset:64
	v_mul_f32_e32 v146, v212, v146
	v_fmac_f32_e32 v146, v181, v23
	global_store_dword v130, v146, s[86:87] offset:128
	v_mul_f32_e32 v147, v212, v147
	v_fmac_f32_e32 v147, v181, v19
	global_store_dword v130, v147, s[86:87] offset:192
	v_mul_f32_e32 v148, v212, v148
	v_fmac_f32_e32 v148, v181, v32
	global_store_dword v131, v148, s[86:87] offset:-4096
	v_mul_f32_e32 v149, v212, v149
	v_fmac_f32_e32 v149, v181, v28
	global_store_dword v131, v149, s[86:87] offset:-4032
	v_mul_f32_e32 v150, v212, v150
	v_fmac_f32_e32 v150, v181, v24
	global_store_dword v131, v150, s[86:87] offset:-3968
	v_mul_f32_e32 v151, v212, v151
	v_fmac_f32_e32 v151, v181, v20
	global_store_dword v131, v151, s[86:87] offset:-3904
	v_mul_f32_e32 v152, v212, v152
	v_fmac_f32_e32 v152, v181, v33
	global_store_dword v131, v152, s[86:87]
	v_mul_f32_e32 v153, v212, v153
	v_fmac_f32_e32 v153, v181, v29
	global_store_dword v131, v153, s[86:87] offset:64
	v_mul_f32_e32 v154, v212, v154
	v_fmac_f32_e32 v154, v181, v25
	global_store_dword v131, v154, s[86:87] offset:128
	v_mul_f32_e32 v155, v212, v155
	v_fmac_f32_e32 v155, v181, v21
	global_store_dword v131, v155, s[86:87] offset:192
	s_waitcnt vmcnt(16)
	v_mul_f32_e32 v156, v212, v156
	v_fmac_f32_e32 v156, v181, v14
	global_store_dword v132, v156, s[86:87] offset:-4096
	v_mul_f32_e32 v157, v212, v157
	v_fmac_f32_e32 v157, v181, v10
	global_store_dword v132, v157, s[86:87] offset:-4032
	v_mul_f32_e32 v158, v212, v158
	v_fmac_f32_e32 v158, v181, v6
	global_store_dword v132, v158, s[86:87] offset:-3968
	v_mul_f32_e32 v159, v212, v159
	v_fmac_f32_e32 v159, v181, v2
	global_store_dword v132, v159, s[86:87] offset:-3904
	v_mul_f32_e32 v160, v212, v160
	v_fmac_f32_e32 v160, v181, v15
	global_store_dword v132, v160, s[86:87]
	v_mul_f32_e32 v161, v212, v161
	v_fmac_f32_e32 v161, v181, v11
	global_store_dword v132, v161, s[86:87] offset:64
	v_mul_f32_e32 v162, v212, v162
	v_fmac_f32_e32 v162, v181, v7
	global_store_dword v132, v162, s[86:87] offset:128
	v_mul_f32_e32 v163, v212, v163
	v_fmac_f32_e32 v163, v181, v3
	global_store_dword v132, v163, s[86:87] offset:192
	v_mul_f32_e32 v164, v212, v164
	v_fmac_f32_e32 v164, v181, v16
	global_store_dword v133, v164, s[86:87] offset:-4096
	v_mul_f32_e32 v165, v212, v165
	v_fmac_f32_e32 v165, v181, v12
	global_store_dword v133, v165, s[86:87] offset:-4032
	v_mul_f32_e32 v166, v212, v166
	v_fmac_f32_e32 v166, v181, v8
	global_store_dword v133, v166, s[86:87] offset:-3968
	v_mul_f32_e32 v167, v212, v167
	v_fmac_f32_e32 v167, v181, v4
	global_store_dword v133, v167, s[86:87] offset:-3904
	v_mul_f32_e32 v168, v212, v168
	v_fmac_f32_e32 v168, v181, v17
	global_store_dword v133, v168, s[86:87]
	v_mul_f32_e32 v169, v212, v169
	v_fmac_f32_e32 v169, v181, v13
	global_store_dword v133, v169, s[86:87] offset:64
	v_mul_f32_e32 v170, v212, v170
	v_fmac_f32_e32 v170, v181, v9
	global_store_dword v133, v170, s[86:87] offset:128
	v_mul_f32_e32 v171, v212, v171
	v_fmac_f32_e32 v171, v181, v5
	global_store_dword v133, v171, s[86:87] offset:192
	s_cbranch_vccnz .LBB0_314

;     ...
;     for (int ms = 0; ms < 8; ++ms) {
;       asm volatile("" ::: "memory");
; #pragma unroll
;       for (int ns = 0; ns < 4; ++ns)
; #pragma unroll
;         for (int j = 0; j < 4; ++j) {
;           int row = m0 + wm * 128 + ms * 16 + quad * 4 + j;
;           int col = n0 + wn * 64 + ns * 16 + l15;
;           const size_t xi = (size_t)row * D + col;
;           const float xv = xin ? xin[xi] : P.out[xi];
;           P.out[xi] = alpha * xv + sc * acc[ms][ns][j];
;         }
.LBB0_318:
	v_add_u32_e32 v136, s8, v183
	v_or_b32_e32 v130, s12, v178
	v_lshlrev_b32_e32 v136, 12, v136
	v_lshl_add_u32 v138, v130, 2, v136
	v_add_u32_e32 v138, 0x1000, v138
	s_and_b64 vcc, exec, s[10:11]
	v_mov_b32_e32 v130, v138
	v_add_u32_e32 v131, 0x2000, v130
	global_load_dword v140, v130, s[86:87] offset:-4096
	global_load_dword v141, v130, s[86:87] offset:-4032
	global_load_dword v142, v130, s[86:87] offset:-3968
	global_load_dword v143, v130, s[86:87] offset:-3904
	global_load_dword v144, v130, s[86:87]
	global_load_dword v145, v130, s[86:87] offset:64
	global_load_dword v146, v130, s[86:87] offset:128
	global_load_dword v147, v130, s[86:87] offset:192
	global_load_dword v148, v131, s[86:87] offset:-4096
	global_load_dword v149, v131, s[86:87] offset:-4032
	global_load_dword v150, v131, s[86:87] offset:-3968
	global_load_dword v151, v131, s[86:87] offset:-3904
	global_load_dword v152, v131, s[86:87]
	global_load_dword v153, v131, s[86:87] offset:64
	global_load_dword v154, v131, s[86:87] offset:128
	global_load_dword v155, v131, s[86:87] offset:192
	v_add_u32_e32 v132, 0x10000, v138
	v_add_u32_e32 v133, 0x2000, v132
	global_load_dword v156, v132, s[86:87] offset:-4096
	global_load_dword v157, v132, s[86:87] offset:-4032
	global_load_dword v158, v132, s[86:87] offset:-3968
	global_load_dword v159, v132, s[86:87] offset:-3904
	global_load_dword v160, v132, s[86:87]
	global_load_dword v161, v132, s[86:87] offset:64
	global_load_dword v162, v132, s[86:87] offset:128
	global_load_dword v163, v132, s[86:87] offset:192
	global_load_dword v164, v133, s[86:87] offset:-4096
	global_load_dword v165, v133, s[86:87] offset:-4032
	global_load_dword v166, v133, s[86:87] offset:-3968
	global_load_dword v167, v133, s[86:87] offset:-3904
	global_load_dword v168, v133, s[86:87]
	global_load_dword v169, v133, s[86:87] offset:64
	global_load_dword v170, v133, s[86:87] offset:128
	global_load_dword v171, v133, s[86:87] offset:192
	s_waitcnt vmcnt(16)
	v_mul_f32_e32 v140, v212, v140
	v_fmac_f32_e32 v140, v181, v126
	global_store_dword v130, v140, s[86:87] offset:-4096
	v_mul_f32_e32 v141, v212, v141
	v_fmac_f32_e32 v141, v181, v122
	global_store_dword v130, v141, s[86:87] offset:-4032
	v_mul_f32_e32 v142, v212, v142
	v_fmac_f32_e32 v142, v181, v118
	global_store_dword v130, v142, s[86:87] offset:-3968
	v_mul_f32_e32 v143, v212, v143
	v_fmac_f32_e32 v143, v181, v114
	global_store_dword v130, v143, s[86:87] offset:-3904
	v_mul_f32_e32 v144, v212, v144
	v_fmac_f32_e32 v144, v181, v127
	global_store_dword v130, v144, s[86:87]
	v_mul_f32_e32 v145, v212, v145
	v_fmac_f32_e32 v145, v181, v123
	global_store_dword v130, v145, s[86:87] offset:64
	v_mul_f32_e32 v146, v212, v146
	v_fmac_f32_e32 v146, v181, v119
	global_store_dword v130, v146, s[86:87] offset:128
	v_mul_f32_e32 v147, v212, v147
	v_fmac_f32_e32 v147, v181, v115
	global_store_dword v130, v147, s[86:87] offset:192
	v_mul_f32_e32 v148, v212, v148
	v_fmac_f32_e32 v148, v181, v128
	global_store_dword v131, v148, s[86:87] offset:-4096
	v_mul_f32_e32 v149, v212, v149
	v_fmac_f32_e32 v149, v181, v124
	global_store_dword v131, v149, s[86:87] offset:-4032
	v_mul_f32_e32 v150, v212, v150
	v_fmac_f32_e32 v150, v181, v120
	global_store_dword v131, v150, s[86:87] offset:-3968
	v_mul_f32_e32 v151, v212, v151
	v_fmac_f32_e32 v151, v181, v116
	global_store_dword v131, v151, s[86:87] offset:-3904
	v_mul_f32_e32 v152, v212, v152
	v_fmac_f32_e32 v152, v181, v129
	global_store_dword v131, v152, s[86:87]
	v_mul_f32_e32 v153, v212, v153
	v_fmac_f32_e32 v153, v181, v125
	global_store_dword v131, v153, s[86:87] offset:64
	v_mul_f32_e32 v154, v212, v154
	v_fmac_f32_e32 v154, v181, v121
	global_store_dword v131, v154, s[86:87] offset:128
	v_mul_f32_e32 v155, v212, v155
	v_fmac_f32_e32 v155, v181, v117
	global_store_dword v131, v155, s[86:87] offset:192
	v_add_u32_e32 v130, 0x20000, v138
	v_add_u32_e32 v131, 0x2000, v130
	global_load_dword v140, v130, s[86:87] offset:-4096
	global_load_dword v141, v130, s[86:87] offset:-4032
	global_load_dword v142, v130, s[86:87] offset:-3968
	global_load_dword v143, v130, s[86:87] offset:-3904
	global_load_dword v144, v130, s[86:87]
	global_load_dword v145, v130, s[86:87] offset:64
	global_load_dword v146, v130, s[86:87] offset:128
	global_load_dword v147, v130, s[86:87] offset:192
	global_load_dword v148, v131, s[86:87] offset:-4096
	global_load_dword v149, v131, s[86:87] offset:-4032
	global_load_dword v150, v131, s[86:87] offset:-3968
	global_load_dword v151, v131, s[86:87] offset:-3904
	global_load_dword v152, v131, s[86:87]
	global_load_dword v153, v131, s[86:87] offset:64
	global_load_dword v154, v131, s[86:87] offset:128
	global_load_dword v155, v131, s[86:87] offset:192
	s_waitcnt vmcnt(32)
;     ...
;     for (int ms = 0; ms < 8; ++ms) {
;       asm volatile("" ::: "memory");
; #pragma unroll
;       for (int ns = 0; ns < 4; ++ns)
; #pragma unroll
;         for (int j = 0; j < 4; ++j) {
;           int row = m0 + wm * 128 + ms * 16 + quad * 4 + j;
;           int col = n0 + wn * 64 + ns * 16 + l15;
;           const size_t xi = (size_t)row * D + col;
;           const float xv = xin ? xin[xi] : P.out[xi];
;           P.out[xi] = alpha * xv + sc * acc[ms][ns][j];
;         }
	v_mul_f32_e32 v156, v212, v156
	v_fmac_f32_e32 v156, v181, v110
	global_store_dword v132, v156, s[86:87] offset:-4096
	v_mul_f32_e32 v157, v212, v157
	v_fmac_f32_e32 v157, v181, v106
	global_store_dword v132, v157, s[86:87] offset:-4032
	v_mul_f32_e32 v158, v212, v158
	v_fmac_f32_e32 v158, v181, v102
	global_store_dword v132, v158, s[86:87] offset:-3968
	v_mul_f32_e32 v159, v212, v159
	v_fmac_f32_e32 v159, v181, v98
	global_store_dword v132, v159, s[86:87] offset:-3904
	v_mul_f32_e32 v160, v212, v160
	v_fmac_f32_e32 v160, v181, v111
	global_store_dword v132, v160, s[86:87]
	v_mul_f32_e32 v161, v212, v161
	v_fmac_f32_e32 v161, v181, v107
	global_store_dword v132, v161, s[86:87] offset:64
	v_mul_f32_e32 v162, v212, v162
	v_fmac_f32_e32 v162, v181, v103
	global_store_dword v132, v162, s[86:87] offset:128
	v_mul_f32_e32 v163, v212, v163
	v_fmac_f32_e32 v163, v181, v99
	global_store_dword v132, v163, s[86:87] offset:192
	v_mul_f32_e32 v164, v212, v164
	v_fmac_f32_e32 v164, v181, v112
	global_store_dword v133, v164, s[86:87] offset:-4096
	v_mul_f32_e32 v165, v212, v165
	v_fmac_f32_e32 v165, v181, v108
	global_store_dword v133, v165, s[86:87] offset:-4032
	v_mul_f32_e32 v166, v212, v166
	v_fmac_f32_e32 v166, v181, v104
	global_store_dword v133, v166, s[86:87] offset:-3968
	v_mul_f32_e32 v167, v212, v167
	v_fmac_f32_e32 v167, v181, v100
	global_store_dword v133, v167, s[86:87] offset:-3904
	v_mul_f32_e32 v168, v212, v168
	v_fmac_f32_e32 v168, v181, v113
	global_store_dword v133, v168, s[86:87]
	v_mul_f32_e32 v169, v212, v169
	v_fmac_f32_e32 v169, v181, v109
	global_store_dword v133, v169, s[86:87] offset:64
	v_mul_f32_e32 v170, v212, v170
	v_fmac_f32_e32 v170, v181, v105
	global_store_dword v133, v170, s[86:87] offset:128
	v_mul_f32_e32 v171, v212, v171
	v_fmac_f32_e32 v171, v181, v101
	global_store_dword v133, v171, s[86:87] offset:192
	v_add_u32_e32 v132, 0x30000, v138
	v_add_u32_e32 v133, 0x2000, v132
	global_load_dword v156, v132, s[86:87] offset:-4096
	global_load_dword v157, v132, s[86:87] offset:-4032
	global_load_dword v158, v132, s[86:87] offset:-3968
	global_load_dword v159, v132, s[86:87] offset:-3904
	global_load_dword v160, v132, s[86:87]
	global_load_dword v161, v132, s[86:87] offset:64
	global_load_dword v162, v132, s[86:87] offset:128
	global_load_dword v163, v132, s[86:87] offset:192
	global_load_dword v164, v133, s[86:87] offset:-4096
	global_load_dword v165, v133, s[86:87] offset:-4032
	global_load_dword v166, v133, s[86:87] offset:-3968
	global_load_dword v167, v133, s[86:87] offset:-3904
	global_load_dword v168, v133, s[86:87]
	global_load_dword v169, v133, s[86:87] offset:64
	global_load_dword v170, v133, s[86:87] offset:128
	global_load_dword v171, v133, s[86:87] offset:192
	s_waitcnt vmcnt(32)
	v_mul_f32_e32 v140, v212, v140
	v_fmac_f32_e32 v140, v181, v94
	global_store_dword v130, v140, s[86:87] offset:-4096
	v_mul_f32_e32 v141, v212, v141
	v_fmac_f32_e32 v141, v181, v90
	global_store_dword v130, v141, s[86:87] offset:-4032
	v_mul_f32_e32 v142, v212, v142
	v_fmac_f32_e32 v142, v181, v86
	global_store_dword v130, v142, s[86:87] offset:-3968
	v_mul_f32_e32 v143, v212, v143
	v_fmac_f32_e32 v143, v181, v82
	global_store_dword v130, v143, s[86:87] offset:-3904
	v_mul_f32_e32 v144, v212, v144
	v_fmac_f32_e32 v144, v181, v95
	global_store_dword v130, v144, s[86:87]
	v_mul_f32_e32 v145, v212, v145
	v_fmac_f32_e32 v145, v181, v91
	global_store_dword v130, v145, s[86:87] offset:64
	v_mul_f32_e32 v146, v212, v146
	v_fmac_f32_e32 v146, v181, v87
	global_store_dword v130, v146, s[86:87] offset:128
	v_mul_f32_e32 v147, v212, v147
	v_fmac_f32_e32 v147, v181, v83
	global_store_dword v130, v147, s[86:87] offset:192
	v_mul_f32_e32 v148, v212, v148
	v_fmac_f32_e32 v148, v181, v96
	global_store_dword v131, v148, s[86:87] offset:-4096
	v_mul_f32_e32 v149, v212, v149
	v_fmac_f32_e32 v149, v181, v92
	global_store_dword v131, v149, s[86:87] offset:-4032
	v_mul_f32_e32 v150, v212, v150
	v_fmac_f32_e32 v150, v181, v88
	global_store_dword v131, v150, s[86:87] offset:-3968
	v_mul_f32_e32 v151, v212, v151
	v_fmac_f32_e32 v151, v181, v84
	global_store_dword v131, v151, s[86:87] offset:-3904
	v_mul_f32_e32 v152, v212, v152
	v_fmac_f32_e32 v152, v181, v97
	global_store_dword v131, v152, s[86:87]
	v_mul_f32_e32 v153, v212, v153
	v_fmac_f32_e32 v153, v181, v93
	global_store_dword v131, v153, s[86:87] offset:64
	v_mul_f32_e32 v154, v212, v154
	v_fmac_f32_e32 v154, v181, v89
	global_store_dword v131, v154, s[86:87] offset:128
	v_mul_f32_e32 v155, v212, v155
	v_fmac_f32_e32 v155, v181, v85
	global_store_dword v131, v155, s[86:87] offset:192
	v_add_u32_e32 v130, 0x40000, v138
	v_add_u32_e32 v131, 0x2000, v130
	global_load_dword v140, v130, s[86:87] offset:-4096
	global_load_dword v141, v130, s[86:87] offset:-4032
	global_load_dword v142, v130, s[86:87] offset:-3968
	global_load_dword v143, v130, s[86:87] offset:-3904
	global_load_dword v144, v130, s[86:87]
	global_load_dword v145, v130, s[86:87] offset:64
	global_load_dword v146, v130, s[86:87] offset:128
	global_load_dword v147, v130, s[86:87] offset:192
	global_load_dword v148, v131, s[86:87] offset:-4096
	global_load_dword v149, v131, s[86:87] offset:-4032
	global_load_dword v150, v131, s[86:87] offset:-3968
	global_load_dword v151, v131, s[86:87] offset:-3904
	global_load_dword v152, v131, s[86:87]
	global_load_dword v153, v131, s[86:87] offset:64
	global_load_dword v154, v131, s[86:87] offset:128
	global_load_dword v155, v131, s[86:87] offset:192
	s_waitcnt vmcnt(32)
;     ...
; #pragma unroll
;     for (int ms = 0; ms < 8; ++ms) {
;       asm volatile("" ::: "memory");
; #pragma unroll
;       for (int ns = 0; ns < 4; ++ns)
; #pragma unroll
;         for (int j = 0; j < 4; ++j) {
;           int row = m0 + wm * 128 + ms * 16 + quad * 4 + j;
;           int col = n0 + wn * 64 + ns * 16 + l15;
;           const size_t xi = (size_t)row * D + col;
;           const float xv = xin ? xin[xi] : P.out[xi];
;           P.out[xi] = alpha * xv + sc * acc[ms][ns][j];
;         }
	v_mul_f32_e32 v156, v212, v156
	v_fmac_f32_e32 v156, v181, v78
	global_store_dword v132, v156, s[86:87] offset:-4096
	v_mul_f32_e32 v157, v212, v157
	v_fmac_f32_e32 v157, v181, v74
	global_store_dword v132, v157, s[86:87] offset:-4032
	v_mul_f32_e32 v158, v212, v158
	v_fmac_f32_e32 v158, v181, v70
	global_store_dword v132, v158, s[86:87] offset:-3968
	v_mul_f32_e32 v159, v212, v159
	v_fmac_f32_e32 v159, v181, v66
	global_store_dword v132, v159, s[86:87] offset:-3904
	v_mul_f32_e32 v160, v212, v160
	v_fmac_f32_e32 v160, v181, v79
	global_store_dword v132, v160, s[86:87]
	v_mul_f32_e32 v161, v212, v161
	v_fmac_f32_e32 v161, v181, v75
	global_store_dword v132, v161, s[86:87] offset:64
	v_mul_f32_e32 v162, v212, v162
	v_fmac_f32_e32 v162, v181, v71
	global_store_dword v132, v162, s[86:87] offset:128
	v_mul_f32_e32 v163, v212, v163
	v_fmac_f32_e32 v163, v181, v67
	global_store_dword v132, v163, s[86:87] offset:192
	v_mul_f32_e32 v164, v212, v164
	v_fmac_f32_e32 v164, v181, v80
	global_store_dword v133, v164, s[86:87] offset:-4096
	v_mul_f32_e32 v165, v212, v165
	v_fmac_f32_e32 v165, v181, v76
	global_store_dword v133, v165, s[86:87] offset:-4032
	v_mul_f32_e32 v166, v212, v166
	v_fmac_f32_e32 v166, v181, v72
	global_store_dword v133, v166, s[86:87] offset:-3968
	v_mul_f32_e32 v167, v212, v167
	v_fmac_f32_e32 v167, v181, v68
	global_store_dword v133, v167, s[86:87] offset:-3904
	v_mul_f32_e32 v168, v212, v168
	v_fmac_f32_e32 v168, v181, v81
	global_store_dword v133, v168, s[86:87]
	v_mul_f32_e32 v169, v212, v169
	v_fmac_f32_e32 v169, v181, v77
	global_store_dword v133, v169, s[86:87] offset:64
	v_mul_f32_e32 v170, v212, v170
	v_fmac_f32_e32 v170, v181, v73
	global_store_dword v133, v170, s[86:87] offset:128
	v_mul_f32_e32 v171, v212, v171
	v_fmac_f32_e32 v171, v181, v69
	global_store_dword v133, v171, s[86:87] offset:192
	v_add_u32_e32 v132, 0x50000, v138
	v_add_u32_e32 v133, 0x2000, v132
	global_load_dword v156, v132, s[86:87] offset:-4096
	global_load_dword v157, v132, s[86:87] offset:-4032
	global_load_dword v158, v132, s[86:87] offset:-3968
	global_load_dword v159, v132, s[86:87] offset:-3904
	global_load_dword v160, v132, s[86:87]
	global_load_dword v161, v132, s[86:87] offset:64
	global_load_dword v162, v132, s[86:87] offset:128
	global_load_dword v163, v132, s[86:87] offset:192
	global_load_dword v164, v133, s[86:87] offset:-4096
	global_load_dword v165, v133, s[86:87] offset:-4032
	global_load_dword v166, v133, s[86:87] offset:-3968
	global_load_dword v167, v133, s[86:87] offset:-3904
	global_load_dword v168, v133, s[86:87]
	global_load_dword v169, v133, s[86:87] offset:64
	global_load_dword v170, v133, s[86:87] offset:128
	global_load_dword v171, v133, s[86:87] offset:192
	s_waitcnt vmcnt(32)
	v_mul_f32_e32 v140, v212, v140
	v_fmac_f32_e32 v140, v181, v62
	global_store_dword v130, v140, s[86:87] offset:-4096
	v_mul_f32_e32 v141, v212, v141
	v_fmac_f32_e32 v141, v181, v58
	global_store_dword v130, v141, s[86:87] offset:-4032
	v_mul_f32_e32 v142, v212, v142
	v_fmac_f32_e32 v142, v181, v54
	global_store_dword v130, v142, s[86:87] offset:-3968
	v_mul_f32_e32 v143, v212, v143
	v_fmac_f32_e32 v143, v181, v50
	global_store_dword v130, v143, s[86:87] offset:-3904
	v_mul_f32_e32 v144, v212, v144
	v_fmac_f32_e32 v144, v181, v63
	global_store_dword v130, v144, s[86:87]
	v_mul_f32_e32 v145, v212, v145
	v_fmac_f32_e32 v145, v181, v59
	global_store_dword v130, v145, s[86:87] offset:64
	v_mul_f32_e32 v146, v212, v146
	v_fmac_f32_e32 v146, v181, v55
	global_store_dword v130, v146, s[86:87] offset:128
	v_mul_f32_e32 v147, v212, v147
	v_fmac_f32_e32 v147, v181, v51
	global_store_dword v130, v147, s[86:87] offset:192
	v_mul_f32_e32 v148, v212, v148
	v_fmac_f32_e32 v148, v181, v64
	global_store_dword v131, v148, s[86:87] offset:-4096
	v_mul_f32_e32 v149, v212, v149
	v_fmac_f32_e32 v149, v181, v60
	global_store_dword v131, v149, s[86:87] offset:-4032
	v_mul_f32_e32 v150, v212, v150
	v_fmac_f32_e32 v150, v181, v56
	global_store_dword v131, v150, s[86:87] offset:-3968
	v_mul_f32_e32 v151, v212, v151
	v_fmac_f32_e32 v151, v181, v52
	global_store_dword v131, v151, s[86:87] offset:-3904
	v_mul_f32_e32 v152, v212, v152
	v_fmac_f32_e32 v152, v181, v65
	global_store_dword v131, v152, s[86:87]
	v_mul_f32_e32 v153, v212, v153
	v_fmac_f32_e32 v153, v181, v61
	global_store_dword v131, v153, s[86:87] offset:64
	v_mul_f32_e32 v154, v212, v154
	v_fmac_f32_e32 v154, v181, v57
	global_store_dword v131, v154, s[86:87] offset:128
	v_mul_f32_e32 v155, v212, v155
	v_fmac_f32_e32 v155, v181, v53
	global_store_dword v131, v155, s[86:87] offset:192
	v_add_u32_e32 v130, 0x60000, v138
	v_add_u32_e32 v131, 0x2000, v130
	global_load_dword v140, v130, s[86:87] offset:-4096
	global_load_dword v141, v130, s[86:87] offset:-4032
	global_load_dword v142, v130, s[86:87] offset:-3968
	global_load_dword v143, v130, s[86:87] offset:-3904
	global_load_dword v144, v130, s[86:87]
	global_load_dword v145, v130, s[86:87] offset:64
	global_load_dword v146, v130, s[86:87] offset:128
	global_load_dword v147, v130, s[86:87] offset:192
	global_load_dword v148, v131, s[86:87] offset:-4096
	global_load_dword v149, v131, s[86:87] offset:-4032
	global_load_dword v150, v131, s[86:87] offset:-3968
	global_load_dword v151, v131, s[86:87] offset:-3904
	global_load_dword v152, v131, s[86:87]
	global_load_dword v153, v131, s[86:87] offset:64
	global_load_dword v154, v131, s[86:87] offset:128
	global_load_dword v155, v131, s[86:87] offset:192
	s_waitcnt vmcnt(32)
;     ...
; #pragma unroll
;     for (int ms = 0; ms < 8; ++ms) {
;       asm volatile("" ::: "memory");
; #pragma unroll
;       for (int ns = 0; ns < 4; ++ns)
; #pragma unroll
;         for (int j = 0; j < 4; ++j) {
;           int row = m0 + wm * 128 + ms * 16 + quad * 4 + j;
;           int col = n0 + wn * 64 + ns * 16 + l15;
;           const size_t xi = (size_t)row * D + col;
;           const float xv = xin ? xin[xi] : P.out[xi];
;           P.out[xi] = alpha * xv + sc * acc[ms][ns][j];
;         }
	v_mul_f32_e32 v156, v212, v156
	v_fmac_f32_e32 v156, v181, v46
	global_store_dword v132, v156, s[86:87] offset:-4096
	v_mul_f32_e32 v157, v212, v157
	v_fmac_f32_e32 v157, v181, v42
	global_store_dword v132, v157, s[86:87] offset:-4032
	v_mul_f32_e32 v158, v212, v158
	v_fmac_f32_e32 v158, v181, v38
	global_store_dword v132, v158, s[86:87] offset:-3968
	v_mul_f32_e32 v159, v212, v159
	v_fmac_f32_e32 v159, v181, v34
	global_store_dword v132, v159, s[86:87] offset:-3904
	v_mul_f32_e32 v160, v212, v160
	v_fmac_f32_e32 v160, v181, v47
	global_store_dword v132, v160, s[86:87]
	v_mul_f32_e32 v161, v212, v161
	v_fmac_f32_e32 v161, v181, v43
	global_store_dword v132, v161, s[86:87] offset:64
	v_mul_f32_e32 v162, v212, v162
	v_fmac_f32_e32 v162, v181, v39
	global_store_dword v132, v162, s[86:87] offset:128
	v_mul_f32_e32 v163, v212, v163
	v_fmac_f32_e32 v163, v181, v35
	global_store_dword v132, v163, s[86:87] offset:192
	v_mul_f32_e32 v164, v212, v164
	v_fmac_f32_e32 v164, v181, v48
	global_store_dword v133, v164, s[86:87] offset:-4096
	v_mul_f32_e32 v165, v212, v165
	v_fmac_f32_e32 v165, v181, v44
	global_store_dword v133, v165, s[86:87] offset:-4032
	v_mul_f32_e32 v166, v212, v166
	v_fmac_f32_e32 v166, v181, v40
	global_store_dword v133, v166, s[86:87] offset:-3968
	v_mul_f32_e32 v167, v212, v167
	v_fmac_f32_e32 v167, v181, v36
	global_store_dword v133, v167, s[86:87] offset:-3904
	v_mul_f32_e32 v168, v212, v168
	v_fmac_f32_e32 v168, v181, v49
	global_store_dword v133, v168, s[86:87]
	v_mul_f32_e32 v169, v212, v169
	v_fmac_f32_e32 v169, v181, v45
	global_store_dword v133, v169, s[86:87] offset:64
	v_mul_f32_e32 v170, v212, v170
	v_fmac_f32_e32 v170, v181, v41
	global_store_dword v133, v170, s[86:87] offset:128
	v_mul_f32_e32 v171, v212, v171
	v_fmac_f32_e32 v171, v181, v37
	global_store_dword v133, v171, s[86:87] offset:192
	v_add_u32_e32 v132, 0x70000, v138
	v_add_u32_e32 v133, 0x2000, v132
	global_load_dword v156, v132, s[86:87] offset:-4096
	global_load_dword v157, v132, s[86:87] offset:-4032
	global_load_dword v158, v132, s[86:87] offset:-3968
	global_load_dword v159, v132, s[86:87] offset:-3904
	global_load_dword v160, v132, s[86:87]
	global_load_dword v161, v132, s[86:87] offset:64
	global_load_dword v162, v132, s[86:87] offset:128
	global_load_dword v163, v132, s[86:87] offset:192
	global_load_dword v164, v133, s[86:87] offset:-4096
	global_load_dword v165, v133, s[86:87] offset:-4032
	global_load_dword v166, v133, s[86:87] offset:-3968
	global_load_dword v167, v133, s[86:87] offset:-3904
	global_load_dword v168, v133, s[86:87]
	global_load_dword v169, v133, s[86:87] offset:64
	global_load_dword v170, v133, s[86:87] offset:128
	global_load_dword v171, v133, s[86:87] offset:192
	s_waitcnt vmcnt(32)
	v_mul_f32_e32 v140, v212, v140
	v_fmac_f32_e32 v140, v181, v30
	global_store_dword v130, v140, s[86:87] offset:-4096
	v_mul_f32_e32 v141, v212, v141
	v_fmac_f32_e32 v141, v181, v26
	global_store_dword v130, v141, s[86:87] offset:-4032
	v_mul_f32_e32 v142, v212, v142
	v_fmac_f32_e32 v142, v181, v22
	global_store_dword v130, v142, s[86:87] offset:-3968
	v_mul_f32_e32 v143, v212, v143
	v_fmac_f32_e32 v143, v181, v18
	global_store_dword v130, v143, s[86:87] offset:-3904
	v_mul_f32_e32 v144, v212, v144
	v_fmac_f32_e32 v144, v181, v31
	global_store_dword v130, v144, s[86:87]
	v_mul_f32_e32 v145, v212, v145
	v_fmac_f32_e32 v145, v181, v27
	global_store_dword v130, v145, s[86:87] offset:64
	v_mul_f32_e32 v146, v212, v146
	v_fmac_f32_e32 v146, v181, v23
	global_store_dword v130, v146, s[86:87] offset:128
	v_mul_f32_e32 v147, v212, v147
	v_fmac_f32_e32 v147, v181, v19
	global_store_dword v130, v147, s[86:87] offset:192
	v_mul_f32_e32 v148, v212, v148
	v_fmac_f32_e32 v148, v181, v32
	global_store_dword v131, v148, s[86:87] offset:-4096
	v_mul_f32_e32 v149, v212, v149
	v_fmac_f32_e32 v149, v181, v28
	global_store_dword v131, v149, s[86:87] offset:-4032
	v_mul_f32_e32 v150, v212, v150
	v_fmac_f32_e32 v150, v181, v24
	global_store_dword v131, v150, s[86:87] offset:-3968
	v_mul_f32_e32 v151, v212, v151
	v_fmac_f32_e32 v151, v181, v20
	global_store_dword v131, v151, s[86:87] offset:-3904
	v_mul_f32_e32 v152, v212, v152
	v_fmac_f32_e32 v152, v181, v33
	global_store_dword v131, v152, s[86:87]
	v_mul_f32_e32 v153, v212, v153
	v_fmac_f32_e32 v153, v181, v29
	global_store_dword v131, v153, s[86:87] offset:64
	v_mul_f32_e32 v154, v212, v154
	v_fmac_f32_e32 v154, v181, v25
	global_store_dword v131, v154, s[86:87] offset:128
	v_mul_f32_e32 v155, v212, v155
	v_fmac_f32_e32 v155, v181, v21
	global_store_dword v131, v155, s[86:87] offset:192
	s_waitcnt vmcnt(16)
	v_mul_f32_e32 v156, v212, v156
	v_fmac_f32_e32 v156, v181, v14
	global_store_dword v132, v156, s[86:87] offset:-4096
	v_mul_f32_e32 v157, v212, v157
	v_fmac_f32_e32 v157, v181, v10
	global_store_dword v132, v157, s[86:87] offset:-4032
	v_mul_f32_e32 v158, v212, v158
	v_fmac_f32_e32 v158, v181, v6
	global_store_dword v132, v158, s[86:87] offset:-3968
	v_mul_f32_e32 v159, v212, v159
	v_fmac_f32_e32 v159, v181, v2
	global_store_dword v132, v159, s[86:87] offset:-3904
	v_mul_f32_e32 v160, v212, v160
	v_fmac_f32_e32 v160, v181, v15
	global_store_dword v132, v160, s[86:87]
	v_mul_f32_e32 v161, v212, v161
	v_fmac_f32_e32 v161, v181, v11
	global_store_dword v132, v161, s[86:87] offset:64
	v_mul_f32_e32 v162, v212, v162
	v_fmac_f32_e32 v162, v181, v7
	global_store_dword v132, v162, s[86:87] offset:128
	v_mul_f32_e32 v163, v212, v163
	v_fmac_f32_e32 v163, v181, v3
	global_store_dword v132, v163, s[86:87] offset:192
	v_mul_f32_e32 v164, v212, v164
	v_fmac_f32_e32 v164, v181, v16
	global_store_dword v133, v164, s[86:87] offset:-4096
	v_mul_f32_e32 v165, v212, v165
	v_fmac_f32_e32 v165, v181, v12
	global_store_dword v133, v165, s[86:87] offset:-4032
	v_mul_f32_e32 v166, v212, v166
	v_fmac_f32_e32 v166, v181, v8
	global_store_dword v133, v166, s[86:87] offset:-3968
	v_mul_f32_e32 v167, v212, v167
	v_fmac_f32_e32 v167, v181, v4
	global_store_dword v133, v167, s[86:87] offset:-3904
	v_mul_f32_e32 v168, v212, v168
	v_fmac_f32_e32 v168, v181, v17
	global_store_dword v133, v168, s[86:87]
	v_mul_f32_e32 v169, v212, v169
	v_fmac_f32_e32 v169, v181, v13
	global_store_dword v133, v169, s[86:87] offset:64
	v_mul_f32_e32 v170, v212, v170
	v_fmac_f32_e32 v170, v181, v9
	global_store_dword v133, v170, s[86:87] offset:128
	v_mul_f32_e32 v171, v212, v171
	v_fmac_f32_e32 v171, v181, v5
	global_store_dword v133, v171, s[86:87] offset:192
	s_cbranch_vccnz .LBB0_343

;     ...
;   for_tiles_pf(128, 8, [&](int mt, int nt, int mtn, int ntn, bool hn, bool first) {
;     f32x4 acc[8][4];
;     zero_acc<8>(acc);
;     int m0 = mt * 256, n0 = nt * 128;
;     if (tiled)
;       gemm_mainloop<8>(acc, RowLin{A + (size_t)m0 * K, 32}, 16384, Wt + (size_t)n0 * K, K, 0, K >> 6, smem, 8192, 32, 4096,
;                        !first, hn, A + (size_t)mtn * 256 * K, Wt + (size_t)ntn * 128 * K);
;     else
;       gemm_mainloop<8>(acc, RowLin{A + (size_t)m0 * K, K}, 64, Wt + (size_t)n0 * K, K, 0, K >> 6, smem, 32, 32, 4096);
; #pragma unroll
;     for (int ms = 0; ms < 8; ++ms) {
;       asm volatile("" ::: "memory");
; #pragma unroll
;       for (int ns = 0; ns < 4; ++ns)
; #pragma unroll
;         for (int j = 0; j < 4; ++j) {
;           int row = m0 + wm * 128 + ms * 16 + quad * 4 + j;
;           int col = n0 + wn * 64 + ns * 16 + l15;
;           const size_t xi = (size_t)row * D + col;
;           const float xv = xin ? xin[xi] : P.out[xi];
;           P.out[xi] = alpha * xv + sc * acc[ms][ns][j];
;         }
.LBB0_2227:
	v_add_u32_e32 v132, s14, v207
	v_lshl_or_b32 v130, s15, 7, v239
	v_lshlrev_b32_e32 v132, 12, v132
	v_lshl_add_u32 v138, v130, 2, v132
	v_add_u32_e32 v138, 0x1000, v138
	s_and_b64 vcc, exec, s[12:13]
	v_mov_b32_e32 v130, v138
	v_add_u32_e32 v131, 0x2000, v130
	global_load_dword v140, v130, s[10:11] offset:-4096
	global_load_dword v141, v130, s[10:11] offset:-4032
	global_load_dword v142, v130, s[10:11] offset:-3968
	global_load_dword v143, v130, s[10:11] offset:-3904
	global_load_dword v144, v130, s[10:11]
	global_load_dword v145, v130, s[10:11] offset:64
	global_load_dword v146, v130, s[10:11] offset:128
	global_load_dword v147, v130, s[10:11] offset:192
	global_load_dword v148, v131, s[10:11] offset:-4096
	global_load_dword v149, v131, s[10:11] offset:-4032
	global_load_dword v150, v131, s[10:11] offset:-3968
	global_load_dword v151, v131, s[10:11] offset:-3904
	global_load_dword v152, v131, s[10:11]
	global_load_dword v153, v131, s[10:11] offset:64
	global_load_dword v154, v131, s[10:11] offset:128
	global_load_dword v155, v131, s[10:11] offset:192
	v_add_u32_e32 v132, 0x10000, v138
	v_add_u32_e32 v133, 0x2000, v132
	global_load_dword v156, v132, s[10:11] offset:-4096
	global_load_dword v157, v132, s[10:11] offset:-4032
	global_load_dword v158, v132, s[10:11] offset:-3968
	global_load_dword v159, v132, s[10:11] offset:-3904
	global_load_dword v160, v132, s[10:11]
	global_load_dword v161, v132, s[10:11] offset:64
	global_load_dword v162, v132, s[10:11] offset:128
	global_load_dword v163, v132, s[10:11] offset:192
	global_load_dword v164, v133, s[10:11] offset:-4096
	global_load_dword v165, v133, s[10:11] offset:-4032
	global_load_dword v166, v133, s[10:11] offset:-3968
	global_load_dword v167, v133, s[10:11] offset:-3904
	global_load_dword v168, v133, s[10:11]
	global_load_dword v169, v133, s[10:11] offset:64
	global_load_dword v170, v133, s[10:11] offset:128
	global_load_dword v171, v133, s[10:11] offset:192
	s_waitcnt vmcnt(16)
	v_mul_f32_e32 v140, v212, v140
	v_fmac_f32_e32 v140, v211, v126
	global_store_dword v130, v140, s[86:87] offset:-4096
	v_mul_f32_e32 v141, v212, v141
	v_fmac_f32_e32 v141, v211, v122
	global_store_dword v130, v141, s[86:87] offset:-4032
	v_mul_f32_e32 v142, v212, v142
	v_fmac_f32_e32 v142, v211, v118
	global_store_dword v130, v142, s[86:87] offset:-3968
	v_mul_f32_e32 v143, v212, v143
	v_fmac_f32_e32 v143, v211, v114
	global_store_dword v130, v143, s[86:87] offset:-3904
	v_mul_f32_e32 v144, v212, v144
	v_fmac_f32_e32 v144, v211, v127
	global_store_dword v130, v144, s[86:87]
	v_mul_f32_e32 v145, v212, v145
	v_fmac_f32_e32 v145, v211, v123
	global_store_dword v130, v145, s[86:87] offset:64
	v_mul_f32_e32 v146, v212, v146
	v_fmac_f32_e32 v146, v211, v119
	global_store_dword v130, v146, s[86:87] offset:128
	v_mul_f32_e32 v147, v212, v147
	v_fmac_f32_e32 v147, v211, v115
	global_store_dword v130, v147, s[86:87] offset:192
	v_mul_f32_e32 v148, v212, v148
	v_fmac_f32_e32 v148, v211, v128
	global_store_dword v131, v148, s[86:87] offset:-4096
	v_mul_f32_e32 v149, v212, v149
	v_fmac_f32_e32 v149, v211, v124
	global_store_dword v131, v149, s[86:87] offset:-4032
	v_mul_f32_e32 v150, v212, v150
	v_fmac_f32_e32 v150, v211, v120
	global_store_dword v131, v150, s[86:87] offset:-3968
	v_mul_f32_e32 v151, v212, v151
	v_fmac_f32_e32 v151, v211, v116
	global_store_dword v131, v151, s[86:87] offset:-3904
	v_mul_f32_e32 v152, v212, v152
	v_fmac_f32_e32 v152, v211, v129
	global_store_dword v131, v152, s[86:87]
	v_mul_f32_e32 v153, v212, v153
	v_fmac_f32_e32 v153, v211, v125
	global_store_dword v131, v153, s[86:87] offset:64
	v_mul_f32_e32 v154, v212, v154
	v_fmac_f32_e32 v154, v211, v121
	global_store_dword v131, v154, s[86:87] offset:128
	v_mul_f32_e32 v155, v212, v155
	v_fmac_f32_e32 v155, v211, v117
	global_store_dword v131, v155, s[86:87] offset:192
	v_add_u32_e32 v130, 0x20000, v138
	v_add_u32_e32 v131, 0x2000, v130
	global_load_dword v140, v130, s[10:11] offset:-4096
	global_load_dword v141, v130, s[10:11] offset:-4032
	global_load_dword v142, v130, s[10:11] offset:-3968
	global_load_dword v143, v130, s[10:11] offset:-3904
	global_load_dword v144, v130, s[10:11]
	global_load_dword v145, v130, s[10:11] offset:64
	global_load_dword v146, v130, s[10:11] offset:128
	global_load_dword v147, v130, s[10:11] offset:192
	global_load_dword v148, v131, s[10:11] offset:-4096
	global_load_dword v149, v131, s[10:11] offset:-4032
	global_load_dword v150, v131, s[10:11] offset:-3968
	global_load_dword v151, v131, s[10:11] offset:-3904
	global_load_dword v152, v131, s[10:11]
	global_load_dword v153, v131, s[10:11] offset:64
	global_load_dword v154, v131, s[10:11] offset:128
	global_load_dword v155, v131, s[10:11] offset:192
	s_waitcnt vmcnt(32)
;     ...
; #pragma unroll
;     for (int ms = 0; ms < 8; ++ms) {
;       asm volatile("" ::: "memory");
; #pragma unroll
;       for (int ns = 0; ns < 4; ++ns)
; #pragma unroll
;         for (int j = 0; j < 4; ++j) {
;           int row = m0 + wm * 128 + ms * 16 + quad * 4 + j;
;           int col = n0 + wn * 64 + ns * 16 + l15;
;           const size_t xi = (size_t)row * D + col;
;           const float xv = xin ? xin[xi] : P.out[xi];
;           P.out[xi] = alpha * xv + sc * acc[ms][ns][j];
;         }
	v_mul_f32_e32 v156, v212, v156
	v_fmac_f32_e32 v156, v211, v110
	global_store_dword v132, v156, s[86:87] offset:-4096
	v_mul_f32_e32 v157, v212, v157
	v_fmac_f32_e32 v157, v211, v106
	global_store_dword v132, v157, s[86:87] offset:-4032
	v_mul_f32_e32 v158, v212, v158
	v_fmac_f32_e32 v158, v211, v102
	global_store_dword v132, v158, s[86:87] offset:-3968
	v_mul_f32_e32 v159, v212, v159
	v_fmac_f32_e32 v159, v211, v98
	global_store_dword v132, v159, s[86:87] offset:-3904
	v_mul_f32_e32 v160, v212, v160
	v_fmac_f32_e32 v160, v211, v111
	global_store_dword v132, v160, s[86:87]
	v_mul_f32_e32 v161, v212, v161
	v_fmac_f32_e32 v161, v211, v107
	global_store_dword v132, v161, s[86:87] offset:64
	v_mul_f32_e32 v162, v212, v162
	v_fmac_f32_e32 v162, v211, v103
	global_store_dword v132, v162, s[86:87] offset:128
	v_mul_f32_e32 v163, v212, v163
	v_fmac_f32_e32 v163, v211, v99
	global_store_dword v132, v163, s[86:87] offset:192
	v_mul_f32_e32 v164, v212, v164
	v_fmac_f32_e32 v164, v211, v112
	global_store_dword v133, v164, s[86:87] offset:-4096
	v_mul_f32_e32 v165, v212, v165
	v_fmac_f32_e32 v165, v211, v108
	global_store_dword v133, v165, s[86:87] offset:-4032
	v_mul_f32_e32 v166, v212, v166
	v_fmac_f32_e32 v166, v211, v104
	global_store_dword v133, v166, s[86:87] offset:-3968
	v_mul_f32_e32 v167, v212, v167
	v_fmac_f32_e32 v167, v211, v100
	global_store_dword v133, v167, s[86:87] offset:-3904
	v_mul_f32_e32 v168, v212, v168
	v_fmac_f32_e32 v168, v211, v113
	global_store_dword v133, v168, s[86:87]
	v_mul_f32_e32 v169, v212, v169
	v_fmac_f32_e32 v169, v211, v109
	global_store_dword v133, v169, s[86:87] offset:64
	v_mul_f32_e32 v170, v212, v170
	v_fmac_f32_e32 v170, v211, v105
	global_store_dword v133, v170, s[86:87] offset:128
	v_mul_f32_e32 v171, v212, v171
	v_fmac_f32_e32 v171, v211, v101
	global_store_dword v133, v171, s[86:87] offset:192
	v_add_u32_e32 v132, 0x30000, v138
	v_add_u32_e32 v133, 0x2000, v132
	global_load_dword v156, v132, s[10:11] offset:-4096
	global_load_dword v157, v132, s[10:11] offset:-4032
	global_load_dword v158, v132, s[10:11] offset:-3968
	global_load_dword v159, v132, s[10:11] offset:-3904
	global_load_dword v160, v132, s[10:11]
	global_load_dword v161, v132, s[10:11] offset:64
	global_load_dword v162, v132, s[10:11] offset:128
	global_load_dword v163, v132, s[10:11] offset:192
	global_load_dword v164, v133, s[10:11] offset:-4096
	global_load_dword v165, v133, s[10:11] offset:-4032
	global_load_dword v166, v133, s[10:11] offset:-3968
	global_load_dword v167, v133, s[10:11] offset:-3904
	global_load_dword v168, v133, s[10:11]
	global_load_dword v169, v133, s[10:11] offset:64
	global_load_dword v170, v133, s[10:11] offset:128
	global_load_dword v171, v133, s[10:11] offset:192
	s_waitcnt vmcnt(32)
	v_mul_f32_e32 v140, v212, v140
	v_fmac_f32_e32 v140, v211, v94
	global_store_dword v130, v140, s[86:87] offset:-4096
	v_mul_f32_e32 v141, v212, v141
	v_fmac_f32_e32 v141, v211, v90
	global_store_dword v130, v141, s[86:87] offset:-4032
	v_mul_f32_e32 v142, v212, v142
	v_fmac_f32_e32 v142, v211, v86
	global_store_dword v130, v142, s[86:87] offset:-3968
	v_mul_f32_e32 v143, v212, v143
	v_fmac_f32_e32 v143, v211, v82
	global_store_dword v130, v143, s[86:87] offset:-3904
	v_mul_f32_e32 v144, v212, v144
	v_fmac_f32_e32 v144, v211, v95
	global_store_dword v130, v144, s[86:87]
	v_mul_f32_e32 v145, v212, v145
	v_fmac_f32_e32 v145, v211, v91
	global_store_dword v130, v145, s[86:87] offset:64
	v_mul_f32_e32 v146, v212, v146
	v_fmac_f32_e32 v146, v211, v87
	global_store_dword v130, v146, s[86:87] offset:128
	v_mul_f32_e32 v147, v212, v147
	v_fmac_f32_e32 v147, v211, v83
	global_store_dword v130, v147, s[86:87] offset:192
	v_mul_f32_e32 v148, v212, v148
	v_fmac_f32_e32 v148, v211, v96
	global_store_dword v131, v148, s[86:87] offset:-4096
	v_mul_f32_e32 v149, v212, v149
	v_fmac_f32_e32 v149, v211, v92
	global_store_dword v131, v149, s[86:87] offset:-4032
	v_mul_f32_e32 v150, v212, v150
	v_fmac_f32_e32 v150, v211, v88
	global_store_dword v131, v150, s[86:87] offset:-3968
	v_mul_f32_e32 v151, v212, v151
	v_fmac_f32_e32 v151, v211, v84
	global_store_dword v131, v151, s[86:87] offset:-3904
	v_mul_f32_e32 v152, v212, v152
	v_fmac_f32_e32 v152, v211, v97
	global_store_dword v131, v152, s[86:87]
	v_mul_f32_e32 v153, v212, v153
	v_fmac_f32_e32 v153, v211, v93
	global_store_dword v131, v153, s[86:87] offset:64
	v_mul_f32_e32 v154, v212, v154
	v_fmac_f32_e32 v154, v211, v89
	global_store_dword v131, v154, s[86:87] offset:128
	v_mul_f32_e32 v155, v212, v155
	v_fmac_f32_e32 v155, v211, v85
	global_store_dword v131, v155, s[86:87] offset:192
	v_add_u32_e32 v130, 0x40000, v138
	v_add_u32_e32 v131, 0x2000, v130
	global_load_dword v140, v130, s[10:11] offset:-4096
	global_load_dword v141, v130, s[10:11] offset:-4032
	global_load_dword v142, v130, s[10:11] offset:-3968
	global_load_dword v143, v130, s[10:11] offset:-3904
	global_load_dword v144, v130, s[10:11]
	global_load_dword v145, v130, s[10:11] offset:64
	global_load_dword v146, v130, s[10:11] offset:128
	global_load_dword v147, v130, s[10:11] offset:192
	global_load_dword v148, v131, s[10:11] offset:-4096
	global_load_dword v149, v131, s[10:11] offset:-4032
	global_load_dword v150, v131, s[10:11] offset:-3968
	global_load_dword v151, v131, s[10:11] offset:-3904
	global_load_dword v152, v131, s[10:11]
	global_load_dword v153, v131, s[10:11] offset:64
	global_load_dword v154, v131, s[10:11] offset:128
	global_load_dword v155, v131, s[10:11] offset:192
	s_waitcnt vmcnt(32)
;     ...
; #pragma unroll
;     for (int ms = 0; ms < 8; ++ms) {
;       asm volatile("" ::: "memory");
; #pragma unroll
;       for (int ns = 0; ns < 4; ++ns)
; #pragma unroll
;         for (int j = 0; j < 4; ++j) {
;           int row = m0 + wm * 128 + ms * 16 + quad * 4 + j;
;           int col = n0 + wn * 64 + ns * 16 + l15;
;           const size_t xi = (size_t)row * D + col;
;           const float xv = xin ? xin[xi] : P.out[xi];
;           P.out[xi] = alpha * xv + sc * acc[ms][ns][j];
;         }
	v_mul_f32_e32 v156, v212, v156
	v_fmac_f32_e32 v156, v211, v78
	global_store_dword v132, v156, s[86:87] offset:-4096
	v_mul_f32_e32 v157, v212, v157
	v_fmac_f32_e32 v157, v211, v74
	global_store_dword v132, v157, s[86:87] offset:-4032
	v_mul_f32_e32 v158, v212, v158
	v_fmac_f32_e32 v158, v211, v70
	global_store_dword v132, v158, s[86:87] offset:-3968
	v_mul_f32_e32 v159, v212, v159
	v_fmac_f32_e32 v159, v211, v66
	global_store_dword v132, v159, s[86:87] offset:-3904
	v_mul_f32_e32 v160, v212, v160
	v_fmac_f32_e32 v160, v211, v79
	global_store_dword v132, v160, s[86:87]
	v_mul_f32_e32 v161, v212, v161
	v_fmac_f32_e32 v161, v211, v75
	global_store_dword v132, v161, s[86:87] offset:64
	v_mul_f32_e32 v162, v212, v162
	v_fmac_f32_e32 v162, v211, v71
	global_store_dword v132, v162, s[86:87] offset:128
	v_mul_f32_e32 v163, v212, v163
	v_fmac_f32_e32 v163, v211, v67
	global_store_dword v132, v163, s[86:87] offset:192
	v_mul_f32_e32 v164, v212, v164
	v_fmac_f32_e32 v164, v211, v80
	global_store_dword v133, v164, s[86:87] offset:-4096
	v_mul_f32_e32 v165, v212, v165
	v_fmac_f32_e32 v165, v211, v76
	global_store_dword v133, v165, s[86:87] offset:-4032
	v_mul_f32_e32 v166, v212, v166
	v_fmac_f32_e32 v166, v211, v72
	global_store_dword v133, v166, s[86:87] offset:-3968
	v_mul_f32_e32 v167, v212, v167
	v_fmac_f32_e32 v167, v211, v68
	global_store_dword v133, v167, s[86:87] offset:-3904
	v_mul_f32_e32 v168, v212, v168
	v_fmac_f32_e32 v168, v211, v81
	global_store_dword v133, v168, s[86:87]
	v_mul_f32_e32 v169, v212, v169
	v_fmac_f32_e32 v169, v211, v77
	global_store_dword v133, v169, s[86:87] offset:64
	v_mul_f32_e32 v170, v212, v170
	v_fmac_f32_e32 v170, v211, v73
	global_store_dword v133, v170, s[86:87] offset:128
	v_mul_f32_e32 v171, v212, v171
	v_fmac_f32_e32 v171, v211, v69
	global_store_dword v133, v171, s[86:87] offset:192
	v_add_u32_e32 v132, 0x50000, v138
	v_add_u32_e32 v133, 0x2000, v132
	global_load_dword v156, v132, s[10:11] offset:-4096
	global_load_dword v157, v132, s[10:11] offset:-4032
	global_load_dword v158, v132, s[10:11] offset:-3968
	global_load_dword v159, v132, s[10:11] offset:-3904
	global_load_dword v160, v132, s[10:11]
	global_load_dword v161, v132, s[10:11] offset:64
	global_load_dword v162, v132, s[10:11] offset:128
	global_load_dword v163, v132, s[10:11] offset:192
	global_load_dword v164, v133, s[10:11] offset:-4096
	global_load_dword v165, v133, s[10:11] offset:-4032
	global_load_dword v166, v133, s[10:11] offset:-3968
	global_load_dword v167, v133, s[10:11] offset:-3904
	global_load_dword v168, v133, s[10:11]
	global_load_dword v169, v133, s[10:11] offset:64
	global_load_dword v170, v133, s[10:11] offset:128
	global_load_dword v171, v133, s[10:11] offset:192
	s_waitcnt vmcnt(32)
	v_mul_f32_e32 v140, v212, v140
	v_fmac_f32_e32 v140, v211, v62
	global_store_dword v130, v140, s[86:87] offset:-4096
	v_mul_f32_e32 v141, v212, v141
	v_fmac_f32_e32 v141, v211, v58
	global_store_dword v130, v141, s[86:87] offset:-4032
	v_mul_f32_e32 v142, v212, v142
	v_fmac_f32_e32 v142, v211, v54
	global_store_dword v130, v142, s[86:87] offset:-3968
	v_mul_f32_e32 v143, v212, v143
	v_fmac_f32_e32 v143, v211, v50
	global_store_dword v130, v143, s[86:87] offset:-3904
	v_mul_f32_e32 v144, v212, v144
	v_fmac_f32_e32 v144, v211, v63
	global_store_dword v130, v144, s[86:87]
	v_mul_f32_e32 v145, v212, v145
	v_fmac_f32_e32 v145, v211, v59
	global_store_dword v130, v145, s[86:87] offset:64
	v_mul_f32_e32 v146, v212, v146
	v_fmac_f32_e32 v146, v211, v55
	global_store_dword v130, v146, s[86:87] offset:128
	v_mul_f32_e32 v147, v212, v147
	v_fmac_f32_e32 v147, v211, v51
	global_store_dword v130, v147, s[86:87] offset:192
	v_mul_f32_e32 v148, v212, v148
	v_fmac_f32_e32 v148, v211, v64
	global_store_dword v131, v148, s[86:87] offset:-4096
	v_mul_f32_e32 v149, v212, v149
	v_fmac_f32_e32 v149, v211, v60
	global_store_dword v131, v149, s[86:87] offset:-4032
	v_mul_f32_e32 v150, v212, v150
	v_fmac_f32_e32 v150, v211, v56
	global_store_dword v131, v150, s[86:87] offset:-3968
	v_mul_f32_e32 v151, v212, v151
	v_fmac_f32_e32 v151, v211, v52
	global_store_dword v131, v151, s[86:87] offset:-3904
	v_mul_f32_e32 v152, v212, v152
	v_fmac_f32_e32 v152, v211, v65
	global_store_dword v131, v152, s[86:87]
	v_mul_f32_e32 v153, v212, v153
	v_fmac_f32_e32 v153, v211, v61
	global_store_dword v131, v153, s[86:87] offset:64
	v_mul_f32_e32 v154, v212, v154
	v_fmac_f32_e32 v154, v211, v57
	global_store_dword v131, v154, s[86:87] offset:128
	v_mul_f32_e32 v155, v212, v155
	v_fmac_f32_e32 v155, v211, v53
	global_store_dword v131, v155, s[86:87] offset:192
	v_add_u32_e32 v130, 0x60000, v138
	v_add_u32_e32 v131, 0x2000, v130
	global_load_dword v140, v130, s[10:11] offset:-4096
	global_load_dword v141, v130, s[10:11] offset:-4032
	global_load_dword v142, v130, s[10:11] offset:-3968
	global_load_dword v143, v130, s[10:11] offset:-3904
	global_load_dword v144, v130, s[10:11]
	global_load_dword v145, v130, s[10:11] offset:64
	global_load_dword v146, v130, s[10:11] offset:128
	global_load_dword v147, v130, s[10:11] offset:192
	global_load_dword v148, v131, s[10:11] offset:-4096
	global_load_dword v149, v131, s[10:11] offset:-4032
	global_load_dword v150, v131, s[10:11] offset:-3968
	global_load_dword v151, v131, s[10:11] offset:-3904
	global_load_dword v152, v131, s[10:11]
	global_load_dword v153, v131, s[10:11] offset:64
	global_load_dword v154, v131, s[10:11] offset:128
	global_load_dword v155, v131, s[10:11] offset:192
	s_waitcnt vmcnt(32)
;     ...
; #pragma unroll
;     for (int ms = 0; ms < 8; ++ms) {
;       asm volatile("" ::: "memory");
; #pragma unroll
;       for (int ns = 0; ns < 4; ++ns)
; #pragma unroll
;         for (int j = 0; j < 4; ++j) {
;           int row = m0 + wm * 128 + ms * 16 + quad * 4 + j;
;           int col = n0 + wn * 64 + ns * 16 + l15;
;           const size_t xi = (size_t)row * D + col;
;           const float xv = xin ? xin[xi] : P.out[xi];
;           P.out[xi] = alpha * xv + sc * acc[ms][ns][j];
;         }
	v_mul_f32_e32 v156, v212, v156
	v_fmac_f32_e32 v156, v211, v46
	global_store_dword v132, v156, s[86:87] offset:-4096
	v_mul_f32_e32 v157, v212, v157
	v_fmac_f32_e32 v157, v211, v42
	global_store_dword v132, v157, s[86:87] offset:-4032
	v_mul_f32_e32 v158, v212, v158
	v_fmac_f32_e32 v158, v211, v38
	global_store_dword v132, v158, s[86:87] offset:-3968
	v_mul_f32_e32 v159, v212, v159
	v_fmac_f32_e32 v159, v211, v34
	global_store_dword v132, v159, s[86:87] offset:-3904
	v_mul_f32_e32 v160, v212, v160
	v_fmac_f32_e32 v160, v211, v47
	global_store_dword v132, v160, s[86:87]
	v_mul_f32_e32 v161, v212, v161
	v_fmac_f32_e32 v161, v211, v43
	global_store_dword v132, v161, s[86:87] offset:64
	v_mul_f32_e32 v162, v212, v162
	v_fmac_f32_e32 v162, v211, v39
	global_store_dword v132, v162, s[86:87] offset:128
	v_mul_f32_e32 v163, v212, v163
	v_fmac_f32_e32 v163, v211, v35
	global_store_dword v132, v163, s[86:87] offset:192
	v_mul_f32_e32 v164, v212, v164
	v_fmac_f32_e32 v164, v211, v48
	global_store_dword v133, v164, s[86:87] offset:-4096
	v_mul_f32_e32 v165, v212, v165
	v_fmac_f32_e32 v165, v211, v44
	global_store_dword v133, v165, s[86:87] offset:-4032
	v_mul_f32_e32 v166, v212, v166
	v_fmac_f32_e32 v166, v211, v40
	global_store_dword v133, v166, s[86:87] offset:-3968
	v_mul_f32_e32 v167, v212, v167
	v_fmac_f32_e32 v167, v211, v36
	global_store_dword v133, v167, s[86:87] offset:-3904
	v_mul_f32_e32 v168, v212, v168
	v_fmac_f32_e32 v168, v211, v49
	global_store_dword v133, v168, s[86:87]
	v_mul_f32_e32 v169, v212, v169
	v_fmac_f32_e32 v169, v211, v45
	global_store_dword v133, v169, s[86:87] offset:64
	v_mul_f32_e32 v170, v212, v170
	v_fmac_f32_e32 v170, v211, v41
	global_store_dword v133, v170, s[86:87] offset:128
	v_mul_f32_e32 v171, v212, v171
	v_fmac_f32_e32 v171, v211, v37
	global_store_dword v133, v171, s[86:87] offset:192
	v_add_u32_e32 v132, 0x70000, v138
	v_add_u32_e32 v133, 0x2000, v132
	global_load_dword v156, v132, s[10:11] offset:-4096
	global_load_dword v157, v132, s[10:11] offset:-4032
	global_load_dword v158, v132, s[10:11] offset:-3968
	global_load_dword v159, v132, s[10:11] offset:-3904
	global_load_dword v160, v132, s[10:11]
	global_load_dword v161, v132, s[10:11] offset:64
	global_load_dword v162, v132, s[10:11] offset:128
	global_load_dword v163, v132, s[10:11] offset:192
	global_load_dword v164, v133, s[10:11] offset:-4096
	global_load_dword v165, v133, s[10:11] offset:-4032
	global_load_dword v166, v133, s[10:11] offset:-3968
	global_load_dword v167, v133, s[10:11] offset:-3904
	global_load_dword v168, v133, s[10:11]
	global_load_dword v169, v133, s[10:11] offset:64
	global_load_dword v170, v133, s[10:11] offset:128
	global_load_dword v171, v133, s[10:11] offset:192
	s_waitcnt vmcnt(32)
	v_mul_f32_e32 v140, v212, v140
	v_fmac_f32_e32 v140, v211, v30
	global_store_dword v130, v140, s[86:87] offset:-4096
	v_mul_f32_e32 v141, v212, v141
	v_fmac_f32_e32 v141, v211, v26
	global_store_dword v130, v141, s[86:87] offset:-4032
	v_mul_f32_e32 v142, v212, v142
	v_fmac_f32_e32 v142, v211, v22
	global_store_dword v130, v142, s[86:87] offset:-3968
	v_mul_f32_e32 v143, v212, v143
	v_fmac_f32_e32 v143, v211, v18
	global_store_dword v130, v143, s[86:87] offset:-3904
	v_mul_f32_e32 v144, v212, v144
	v_fmac_f32_e32 v144, v211, v31
	global_store_dword v130, v144, s[86:87]
	v_mul_f32_e32 v145, v212, v145
	v_fmac_f32_e32 v145, v211, v27
	global_store_dword v130, v145, s[86:87] offset:64
	v_mul_f32_e32 v146, v212, v146
	v_fmac_f32_e32 v146, v211, v23
	global_store_dword v130, v146, s[86:87] offset:128
	v_mul_f32_e32 v147, v212, v147
	v_fmac_f32_e32 v147, v211, v19
	global_store_dword v130, v147, s[86:87] offset:192
	v_mul_f32_e32 v148, v212, v148
	v_fmac_f32_e32 v148, v211, v32
	global_store_dword v131, v148, s[86:87] offset:-4096
	v_mul_f32_e32 v149, v212, v149
	v_fmac_f32_e32 v149, v211, v28
	global_store_dword v131, v149, s[86:87] offset:-4032
	v_mul_f32_e32 v150, v212, v150
	v_fmac_f32_e32 v150, v211, v24
	global_store_dword v131, v150, s[86:87] offset:-3968
	v_mul_f32_e32 v151, v212, v151
	v_fmac_f32_e32 v151, v211, v20
	global_store_dword v131, v151, s[86:87] offset:-3904
	v_mul_f32_e32 v152, v212, v152
	v_fmac_f32_e32 v152, v211, v33
	global_store_dword v131, v152, s[86:87]
	v_mul_f32_e32 v153, v212, v153
	v_fmac_f32_e32 v153, v211, v29
	global_store_dword v131, v153, s[86:87] offset:64
	v_mul_f32_e32 v154, v212, v154
	v_fmac_f32_e32 v154, v211, v25
	global_store_dword v131, v154, s[86:87] offset:128
	v_mul_f32_e32 v155, v212, v155
	v_fmac_f32_e32 v155, v211, v21
	global_store_dword v131, v155, s[86:87] offset:192
	s_waitcnt vmcnt(16)
	v_mul_f32_e32 v156, v212, v156
	v_fmac_f32_e32 v156, v211, v14
	global_store_dword v132, v156, s[86:87] offset:-4096
	v_mul_f32_e32 v157, v212, v157
	v_fmac_f32_e32 v157, v211, v10
	global_store_dword v132, v157, s[86:87] offset:-4032
	v_mul_f32_e32 v158, v212, v158
	v_fmac_f32_e32 v158, v211, v6
	global_store_dword v132, v158, s[86:87] offset:-3968
	v_mul_f32_e32 v159, v212, v159
	v_fmac_f32_e32 v159, v211, v2
	global_store_dword v132, v159, s[86:87] offset:-3904
	v_mul_f32_e32 v160, v212, v160
	v_fmac_f32_e32 v160, v211, v15
	global_store_dword v132, v160, s[86:87]
	v_mul_f32_e32 v161, v212, v161
	v_fmac_f32_e32 v161, v211, v11
	global_store_dword v132, v161, s[86:87] offset:64
	v_mul_f32_e32 v162, v212, v162
	v_fmac_f32_e32 v162, v211, v7
	global_store_dword v132, v162, s[86:87] offset:128
	v_mul_f32_e32 v163, v212, v163
	v_fmac_f32_e32 v163, v211, v3
	global_store_dword v132, v163, s[86:87] offset:192
	v_mul_f32_e32 v164, v212, v164
	v_fmac_f32_e32 v164, v211, v16
	global_store_dword v133, v164, s[86:87] offset:-4096
	v_mul_f32_e32 v165, v212, v165
	v_fmac_f32_e32 v165, v211, v12
	global_store_dword v133, v165, s[86:87] offset:-4032
	v_mul_f32_e32 v166, v212, v166
	v_fmac_f32_e32 v166, v211, v8
	global_store_dword v133, v166, s[86:87] offset:-3968
	v_mul_f32_e32 v167, v212, v167
	v_fmac_f32_e32 v167, v211, v4
	global_store_dword v133, v167, s[86:87] offset:-3904
	v_mul_f32_e32 v168, v212, v168
	v_fmac_f32_e32 v168, v211, v17
	global_store_dword v133, v168, s[86:87]
	v_mul_f32_e32 v169, v212, v169
	v_fmac_f32_e32 v169, v211, v13
	global_store_dword v133, v169, s[86:87] offset:64
	v_mul_f32_e32 v170, v212, v170
	v_fmac_f32_e32 v170, v211, v9
	global_store_dword v133, v170, s[86:87] offset:128
	v_mul_f32_e32 v171, v212, v171
	v_fmac_f32_e32 v171, v211, v5
	global_store_dword v133, v171, s[86:87] offset:192
	s_cbranch_vccnz .LBB0_2252

;     ...
;   for_tiles_pf(128, 8, [&](int mt, int nt, int mtn, int ntn, bool hn, bool first) {
;     f32x4 acc[8][4];
;     zero_acc<8>(acc);
;     int m0 = mt * 256, n0 = nt * 128;
;     if (tiled)
;       gemm_mainloop<8>(acc, RowLin{A + (size_t)m0 * K, 32}, 16384, Wt + (size_t)n0 * K, K, 0, K >> 6, smem, 8192, 32, 4096,
;                        !first, hn, A + (size_t)mtn * 256 * K, Wt + (size_t)ntn * 128 * K);
;     else
;       gemm_mainloop<8>(acc, RowLin{A + (size_t)m0 * K, K}, 64, Wt + (size_t)n0 * K, K, 0, K >> 6, smem, 32, 32, 4096);
; #pragma unroll
;     for (int ms = 0; ms < 8; ++ms) {
;       asm volatile("" ::: "memory");
; #pragma unroll
;       for (int ns = 0; ns < 4; ++ns)
; #pragma unroll
;         for (int j = 0; j < 4; ++j) {
;           int row = m0 + wm * 128 + ms * 16 + quad * 4 + j;
;           int col = n0 + wn * 64 + ns * 16 + l15;
;           const size_t xi = (size_t)row * D + col;
;           const float xv = xin ? xin[xi] : P.out[xi];
;           P.out[xi] = alpha * xv + sc * acc[ms][ns][j];
;         }
.LBB0_2281:
	v_add_u32_e32 v132, s14, v178
	v_or_b32_e32 v130, s15, v183
	v_lshlrev_b32_e32 v132, 12, v132
	v_lshl_add_u32 v138, v130, 2, v132
	v_add_u32_e32 v138, 0x1000, v138
	v_mov_b32_e32 v130, v138
	v_add_u32_e32 v131, 0x2000, v130
	global_load_dword v140, v130, s[8:9] offset:-4096
	global_load_dword v141, v130, s[8:9] offset:-4032
	global_load_dword v142, v130, s[8:9] offset:-3968
	global_load_dword v143, v130, s[8:9] offset:-3904
	global_load_dword v144, v130, s[8:9]
	global_load_dword v145, v130, s[8:9] offset:64
	global_load_dword v146, v130, s[8:9] offset:128
	global_load_dword v147, v130, s[8:9] offset:192
	global_load_dword v148, v131, s[8:9] offset:-4096
	global_load_dword v149, v131, s[8:9] offset:-4032
	global_load_dword v150, v131, s[8:9] offset:-3968
	global_load_dword v151, v131, s[8:9] offset:-3904
	global_load_dword v152, v131, s[8:9]
	global_load_dword v153, v131, s[8:9] offset:64
	global_load_dword v154, v131, s[8:9] offset:128
	global_load_dword v155, v131, s[8:9] offset:192
	v_add_u32_e32 v132, 0x10000, v138
	v_add_u32_e32 v133, 0x2000, v132
	global_load_dword v156, v132, s[8:9] offset:-4096
	global_load_dword v157, v132, s[8:9] offset:-4032
	global_load_dword v158, v132, s[8:9] offset:-3968
	global_load_dword v159, v132, s[8:9] offset:-3904
	global_load_dword v160, v132, s[8:9]
	global_load_dword v161, v132, s[8:9] offset:64
	global_load_dword v162, v132, s[8:9] offset:128
	global_load_dword v163, v132, s[8:9] offset:192
	global_load_dword v164, v133, s[8:9] offset:-4096
	global_load_dword v165, v133, s[8:9] offset:-4032
	global_load_dword v166, v133, s[8:9] offset:-3968
	global_load_dword v167, v133, s[8:9] offset:-3904
	global_load_dword v168, v133, s[8:9]
	global_load_dword v169, v133, s[8:9] offset:64
	global_load_dword v170, v133, s[8:9] offset:128
	global_load_dword v171, v133, s[8:9] offset:192
	s_waitcnt vmcnt(16)
	v_mul_f32_e32 v140, v212, v140
	v_fmac_f32_e32 v140, v211, v126
	global_store_dword v130, v140, s[86:87] offset:-4096
	v_mul_f32_e32 v141, v212, v141
	v_fmac_f32_e32 v141, v211, v122
	global_store_dword v130, v141, s[86:87] offset:-4032
	v_mul_f32_e32 v142, v212, v142
	v_fmac_f32_e32 v142, v211, v118
	global_store_dword v130, v142, s[86:87] offset:-3968
	v_mul_f32_e32 v143, v212, v143
	v_fmac_f32_e32 v143, v211, v114
	global_store_dword v130, v143, s[86:87] offset:-3904
	v_mul_f32_e32 v144, v212, v144
	v_fmac_f32_e32 v144, v211, v127
	global_store_dword v130, v144, s[86:87]
	v_mul_f32_e32 v145, v212, v145
	v_fmac_f32_e32 v145, v211, v123
	global_store_dword v130, v145, s[86:87] offset:64
	v_mul_f32_e32 v146, v212, v146
	v_fmac_f32_e32 v146, v211, v119
	global_store_dword v130, v146, s[86:87] offset:128
	v_mul_f32_e32 v147, v212, v147
	v_fmac_f32_e32 v147, v211, v115
	global_store_dword v130, v147, s[86:87] offset:192
	v_mul_f32_e32 v148, v212, v148
	v_fmac_f32_e32 v148, v211, v128
	global_store_dword v131, v148, s[86:87] offset:-4096
	v_mul_f32_e32 v149, v212, v149
	v_fmac_f32_e32 v149, v211, v124
	global_store_dword v131, v149, s[86:87] offset:-4032
	v_mul_f32_e32 v150, v212, v150
	v_fmac_f32_e32 v150, v211, v120
	global_store_dword v131, v150, s[86:87] offset:-3968
	v_mul_f32_e32 v151, v212, v151
	v_fmac_f32_e32 v151, v211, v116
	global_store_dword v131, v151, s[86:87] offset:-3904
	v_mul_f32_e32 v152, v212, v152
	v_fmac_f32_e32 v152, v211, v129
	global_store_dword v131, v152, s[86:87]
	v_mul_f32_e32 v153, v212, v153
	v_fmac_f32_e32 v153, v211, v125
	global_store_dword v131, v153, s[86:87] offset:64
	v_mul_f32_e32 v154, v212, v154
	v_fmac_f32_e32 v154, v211, v121
	global_store_dword v131, v154, s[86:87] offset:128
	v_mul_f32_e32 v155, v212, v155
	v_fmac_f32_e32 v155, v211, v117
	global_store_dword v131, v155, s[86:87] offset:192
	v_add_u32_e32 v130, 0x20000, v138
	v_add_u32_e32 v131, 0x2000, v130
	global_load_dword v140, v130, s[8:9] offset:-4096
	global_load_dword v141, v130, s[8:9] offset:-4032
	global_load_dword v142, v130, s[8:9] offset:-3968
	global_load_dword v143, v130, s[8:9] offset:-3904
	global_load_dword v144, v130, s[8:9]
	global_load_dword v145, v130, s[8:9] offset:64
	global_load_dword v146, v130, s[8:9] offset:128
	global_load_dword v147, v130, s[8:9] offset:192
	global_load_dword v148, v131, s[8:9] offset:-4096
	global_load_dword v149, v131, s[8:9] offset:-4032
	global_load_dword v150, v131, s[8:9] offset:-3968
	global_load_dword v151, v131, s[8:9] offset:-3904
	global_load_dword v152, v131, s[8:9]
	global_load_dword v153, v131, s[8:9] offset:64
	global_load_dword v154, v131, s[8:9] offset:128
	global_load_dword v155, v131, s[8:9] offset:192
	s_waitcnt vmcnt(32)
;     ...
; #pragma unroll
;     for (int ms = 0; ms < 8; ++ms) {
;       asm volatile("" ::: "memory");
; #pragma unroll
;       for (int ns = 0; ns < 4; ++ns)
; #pragma unroll
;         for (int j = 0; j < 4; ++j) {
;           int row = m0 + wm * 128 + ms * 16 + quad * 4 + j;
;           int col = n0 + wn * 64 + ns * 16 + l15;
;           const size_t xi = (size_t)row * D + col;
;           const float xv = xin ? xin[xi] : P.out[xi];
;           P.out[xi] = alpha * xv + sc * acc[ms][ns][j];
;         }
	v_mul_f32_e32 v156, v212, v156
	v_fmac_f32_e32 v156, v211, v110
	global_store_dword v132, v156, s[86:87] offset:-4096
	v_mul_f32_e32 v157, v212, v157
	v_fmac_f32_e32 v157, v211, v106
	global_store_dword v132, v157, s[86:87] offset:-4032
	v_mul_f32_e32 v158, v212, v158
	v_fmac_f32_e32 v158, v211, v102
	global_store_dword v132, v158, s[86:87] offset:-3968
	v_mul_f32_e32 v159, v212, v159
	v_fmac_f32_e32 v159, v211, v98
	global_store_dword v132, v159, s[86:87] offset:-3904
	v_mul_f32_e32 v160, v212, v160
	v_fmac_f32_e32 v160, v211, v111
	global_store_dword v132, v160, s[86:87]
	v_mul_f32_e32 v161, v212, v161
	v_fmac_f32_e32 v161, v211, v107
	global_store_dword v132, v161, s[86:87] offset:64
	v_mul_f32_e32 v162, v212, v162
	v_fmac_f32_e32 v162, v211, v103
	global_store_dword v132, v162, s[86:87] offset:128
	v_mul_f32_e32 v163, v212, v163
	v_fmac_f32_e32 v163, v211, v99
	global_store_dword v132, v163, s[86:87] offset:192
	v_mul_f32_e32 v164, v212, v164
	v_fmac_f32_e32 v164, v211, v112
	global_store_dword v133, v164, s[86:87] offset:-4096
	v_mul_f32_e32 v165, v212, v165
	v_fmac_f32_e32 v165, v211, v108
	global_store_dword v133, v165, s[86:87] offset:-4032
	v_mul_f32_e32 v166, v212, v166
	v_fmac_f32_e32 v166, v211, v104
	global_store_dword v133, v166, s[86:87] offset:-3968
	v_mul_f32_e32 v167, v212, v167
	v_fmac_f32_e32 v167, v211, v100
	global_store_dword v133, v167, s[86:87] offset:-3904
	v_mul_f32_e32 v168, v212, v168
	v_fmac_f32_e32 v168, v211, v113
	global_store_dword v133, v168, s[86:87]
	v_mul_f32_e32 v169, v212, v169
	v_fmac_f32_e32 v169, v211, v109
	global_store_dword v133, v169, s[86:87] offset:64
	v_mul_f32_e32 v170, v212, v170
	v_fmac_f32_e32 v170, v211, v105
	global_store_dword v133, v170, s[86:87] offset:128
	v_mul_f32_e32 v171, v212, v171
	v_fmac_f32_e32 v171, v211, v101
	global_store_dword v133, v171, s[86:87] offset:192
	v_add_u32_e32 v132, 0x30000, v138
	v_add_u32_e32 v133, 0x2000, v132
	global_load_dword v156, v132, s[8:9] offset:-4096
	global_load_dword v157, v132, s[8:9] offset:-4032
	global_load_dword v158, v132, s[8:9] offset:-3968
	global_load_dword v159, v132, s[8:9] offset:-3904
	global_load_dword v160, v132, s[8:9]
	global_load_dword v161, v132, s[8:9] offset:64
	global_load_dword v162, v132, s[8:9] offset:128
	global_load_dword v163, v132, s[8:9] offset:192
	global_load_dword v164, v133, s[8:9] offset:-4096
	global_load_dword v165, v133, s[8:9] offset:-4032
	global_load_dword v166, v133, s[8:9] offset:-3968
	global_load_dword v167, v133, s[8:9] offset:-3904
	global_load_dword v168, v133, s[8:9]
	global_load_dword v169, v133, s[8:9] offset:64
	global_load_dword v170, v133, s[8:9] offset:128
	global_load_dword v171, v133, s[8:9] offset:192
	s_waitcnt vmcnt(32)
	v_mul_f32_e32 v140, v212, v140
	v_fmac_f32_e32 v140, v211, v94
	global_store_dword v130, v140, s[86:87] offset:-4096
	v_mul_f32_e32 v141, v212, v141
	v_fmac_f32_e32 v141, v211, v90
	global_store_dword v130, v141, s[86:87] offset:-4032
	v_mul_f32_e32 v142, v212, v142
	v_fmac_f32_e32 v142, v211, v86
	global_store_dword v130, v142, s[86:87] offset:-3968
	v_mul_f32_e32 v143, v212, v143
	v_fmac_f32_e32 v143, v211, v82
	global_store_dword v130, v143, s[86:87] offset:-3904
	v_mul_f32_e32 v144, v212, v144
	v_fmac_f32_e32 v144, v211, v95
	global_store_dword v130, v144, s[86:87]
	v_mul_f32_e32 v145, v212, v145
	v_fmac_f32_e32 v145, v211, v91
	global_store_dword v130, v145, s[86:87] offset:64
	v_mul_f32_e32 v146, v212, v146
	v_fmac_f32_e32 v146, v211, v87
	global_store_dword v130, v146, s[86:87] offset:128
	v_mul_f32_e32 v147, v212, v147
	v_fmac_f32_e32 v147, v211, v83
	global_store_dword v130, v147, s[86:87] offset:192
	v_mul_f32_e32 v148, v212, v148
	v_fmac_f32_e32 v148, v211, v96
	global_store_dword v131, v148, s[86:87] offset:-4096
	v_mul_f32_e32 v149, v212, v149
	v_fmac_f32_e32 v149, v211, v92
	global_store_dword v131, v149, s[86:87] offset:-4032
	v_mul_f32_e32 v150, v212, v150
	v_fmac_f32_e32 v150, v211, v88
	global_store_dword v131, v150, s[86:87] offset:-3968
	v_mul_f32_e32 v151, v212, v151
	v_fmac_f32_e32 v151, v211, v84
	global_store_dword v131, v151, s[86:87] offset:-3904
	v_mul_f32_e32 v152, v212, v152
	v_fmac_f32_e32 v152, v211, v97
	global_store_dword v131, v152, s[86:87]
	v_mul_f32_e32 v153, v212, v153
	v_fmac_f32_e32 v153, v211, v93
	global_store_dword v131, v153, s[86:87] offset:64
	v_mul_f32_e32 v154, v212, v154
	v_fmac_f32_e32 v154, v211, v89
	global_store_dword v131, v154, s[86:87] offset:128
	v_mul_f32_e32 v155, v212, v155
	v_fmac_f32_e32 v155, v211, v85
	global_store_dword v131, v155, s[86:87] offset:192
	v_add_u32_e32 v130, 0x40000, v138
	v_add_u32_e32 v131, 0x2000, v130
	global_load_dword v140, v130, s[8:9] offset:-4096
	global_load_dword v141, v130, s[8:9] offset:-4032
	global_load_dword v142, v130, s[8:9] offset:-3968
	global_load_dword v143, v130, s[8:9] offset:-3904
	global_load_dword v144, v130, s[8:9]
	global_load_dword v145, v130, s[8:9] offset:64
	global_load_dword v146, v130, s[8:9] offset:128
	global_load_dword v147, v130, s[8:9] offset:192
	global_load_dword v148, v131, s[8:9] offset:-4096
	global_load_dword v149, v131, s[8:9] offset:-4032
	global_load_dword v150, v131, s[8:9] offset:-3968
	global_load_dword v151, v131, s[8:9] offset:-3904
	global_load_dword v152, v131, s[8:9]
	global_load_dword v153, v131, s[8:9] offset:64
	global_load_dword v154, v131, s[8:9] offset:128
	global_load_dword v155, v131, s[8:9] offset:192
	s_waitcnt vmcnt(32)
;     ...
; #pragma unroll
;     for (int ms = 0; ms < 8; ++ms) {
;       asm volatile("" ::: "memory");
; #pragma unroll
;       for (int ns = 0; ns < 4; ++ns)
; #pragma unroll
;         for (int j = 0; j < 4; ++j) {
;           int row = m0 + wm * 128 + ms * 16 + quad * 4 + j;
;           int col = n0 + wn * 64 + ns * 16 + l15;
;           const size_t xi = (size_t)row * D + col;
;           const float xv = xin ? xin[xi] : P.out[xi];
;           P.out[xi] = alpha * xv + sc * acc[ms][ns][j];
;         }
	v_mul_f32_e32 v156, v212, v156
	v_fmac_f32_e32 v156, v211, v78
	global_store_dword v132, v156, s[86:87] offset:-4096
	v_mul_f32_e32 v157, v212, v157
	v_fmac_f32_e32 v157, v211, v74
	global_store_dword v132, v157, s[86:87] offset:-4032
	v_mul_f32_e32 v158, v212, v158
	v_fmac_f32_e32 v158, v211, v70
	global_store_dword v132, v158, s[86:87] offset:-3968
	v_mul_f32_e32 v159, v212, v159
	v_fmac_f32_e32 v159, v211, v66
	global_store_dword v132, v159, s[86:87] offset:-3904
	v_mul_f32_e32 v160, v212, v160
	v_fmac_f32_e32 v160, v211, v79
	global_store_dword v132, v160, s[86:87]
	v_mul_f32_e32 v161, v212, v161
	v_fmac_f32_e32 v161, v211, v75
	global_store_dword v132, v161, s[86:87] offset:64
	v_mul_f32_e32 v162, v212, v162
	v_fmac_f32_e32 v162, v211, v71
	global_store_dword v132, v162, s[86:87] offset:128
	v_mul_f32_e32 v163, v212, v163
	v_fmac_f32_e32 v163, v211, v67
	global_store_dword v132, v163, s[86:87] offset:192
	v_mul_f32_e32 v164, v212, v164
	v_fmac_f32_e32 v164, v211, v80
	global_store_dword v133, v164, s[86:87] offset:-4096
	v_mul_f32_e32 v165, v212, v165
	v_fmac_f32_e32 v165, v211, v76
	global_store_dword v133, v165, s[86:87] offset:-4032
	v_mul_f32_e32 v166, v212, v166
	v_fmac_f32_e32 v166, v211, v72
	global_store_dword v133, v166, s[86:87] offset:-3968
	v_mul_f32_e32 v167, v212, v167
	v_fmac_f32_e32 v167, v211, v68
	global_store_dword v133, v167, s[86:87] offset:-3904
	v_mul_f32_e32 v168, v212, v168
	v_fmac_f32_e32 v168, v211, v81
	global_store_dword v133, v168, s[86:87]
	v_mul_f32_e32 v169, v212, v169
	v_fmac_f32_e32 v169, v211, v77
	global_store_dword v133, v169, s[86:87] offset:64
	v_mul_f32_e32 v170, v212, v170
	v_fmac_f32_e32 v170, v211, v73
	global_store_dword v133, v170, s[86:87] offset:128
	v_mul_f32_e32 v171, v212, v171
	v_fmac_f32_e32 v171, v211, v69
	global_store_dword v133, v171, s[86:87] offset:192
	v_add_u32_e32 v132, 0x50000, v138
	v_add_u32_e32 v133, 0x2000, v132
	global_load_dword v156, v132, s[8:9] offset:-4096
	global_load_dword v157, v132, s[8:9] offset:-4032
	global_load_dword v158, v132, s[8:9] offset:-3968
	global_load_dword v159, v132, s[8:9] offset:-3904
	global_load_dword v160, v132, s[8:9]
	global_load_dword v161, v132, s[8:9] offset:64
	global_load_dword v162, v132, s[8:9] offset:128
	global_load_dword v163, v132, s[8:9] offset:192
	global_load_dword v164, v133, s[8:9] offset:-4096
	global_load_dword v165, v133, s[8:9] offset:-4032
	global_load_dword v166, v133, s[8:9] offset:-3968
	global_load_dword v167, v133, s[8:9] offset:-3904
	global_load_dword v168, v133, s[8:9]
	global_load_dword v169, v133, s[8:9] offset:64
	global_load_dword v170, v133, s[8:9] offset:128
	global_load_dword v171, v133, s[8:9] offset:192
	s_waitcnt vmcnt(32)
	v_mul_f32_e32 v140, v212, v140
	v_fmac_f32_e32 v140, v211, v62
	global_store_dword v130, v140, s[86:87] offset:-4096
	v_mul_f32_e32 v141, v212, v141
	v_fmac_f32_e32 v141, v211, v58
	global_store_dword v130, v141, s[86:87] offset:-4032
	v_mul_f32_e32 v142, v212, v142
	v_fmac_f32_e32 v142, v211, v54
	global_store_dword v130, v142, s[86:87] offset:-3968
	v_mul_f32_e32 v143, v212, v143
	v_fmac_f32_e32 v143, v211, v50
	global_store_dword v130, v143, s[86:87] offset:-3904
	v_mul_f32_e32 v144, v212, v144
	v_fmac_f32_e32 v144, v211, v63
	global_store_dword v130, v144, s[86:87]
	v_mul_f32_e32 v145, v212, v145
	v_fmac_f32_e32 v145, v211, v59
	global_store_dword v130, v145, s[86:87] offset:64
	v_mul_f32_e32 v146, v212, v146
	v_fmac_f32_e32 v146, v211, v55
	global_store_dword v130, v146, s[86:87] offset:128
	v_mul_f32_e32 v147, v212, v147
	v_fmac_f32_e32 v147, v211, v51
	global_store_dword v130, v147, s[86:87] offset:192
	v_mul_f32_e32 v148, v212, v148
	v_fmac_f32_e32 v148, v211, v64
	global_store_dword v131, v148, s[86:87] offset:-4096
	v_mul_f32_e32 v149, v212, v149
	v_fmac_f32_e32 v149, v211, v60
	global_store_dword v131, v149, s[86:87] offset:-4032
	v_mul_f32_e32 v150, v212, v150
	v_fmac_f32_e32 v150, v211, v56
	global_store_dword v131, v150, s[86:87] offset:-3968
	v_mul_f32_e32 v151, v212, v151
	v_fmac_f32_e32 v151, v211, v52
	global_store_dword v131, v151, s[86:87] offset:-3904
	v_mul_f32_e32 v152, v212, v152
	v_fmac_f32_e32 v152, v211, v65
	global_store_dword v131, v152, s[86:87]
	v_mul_f32_e32 v153, v212, v153
	v_fmac_f32_e32 v153, v211, v61
	global_store_dword v131, v153, s[86:87] offset:64
	v_mul_f32_e32 v154, v212, v154
	v_fmac_f32_e32 v154, v211, v57
	global_store_dword v131, v154, s[86:87] offset:128
	v_mul_f32_e32 v155, v212, v155
	v_fmac_f32_e32 v155, v211, v53
	global_store_dword v131, v155, s[86:87] offset:192
	v_add_u32_e32 v130, 0x60000, v138
	v_add_u32_e32 v131, 0x2000, v130
	global_load_dword v140, v130, s[8:9] offset:-4096
	global_load_dword v141, v130, s[8:9] offset:-4032
	global_load_dword v142, v130, s[8:9] offset:-3968
	global_load_dword v143, v130, s[8:9] offset:-3904
	global_load_dword v144, v130, s[8:9]
	global_load_dword v145, v130, s[8:9] offset:64
	global_load_dword v146, v130, s[8:9] offset:128
	global_load_dword v147, v130, s[8:9] offset:192
	global_load_dword v148, v131, s[8:9] offset:-4096
	global_load_dword v149, v131, s[8:9] offset:-4032
	global_load_dword v150, v131, s[8:9] offset:-3968
	global_load_dword v151, v131, s[8:9] offset:-3904
	global_load_dword v152, v131, s[8:9]
	global_load_dword v153, v131, s[8:9] offset:64
	global_load_dword v154, v131, s[8:9] offset:128
	global_load_dword v155, v131, s[8:9] offset:192
	s_waitcnt vmcnt(32)
;     ...
; #pragma unroll
;     for (int ms = 0; ms < 8; ++ms) {
;       asm volatile("" ::: "memory");
; #pragma unroll
;       for (int ns = 0; ns < 4; ++ns)
; #pragma unroll
;         for (int j = 0; j < 4; ++j) {
;           int row = m0 + wm * 128 + ms * 16 + quad * 4 + j;
;           int col = n0 + wn * 64 + ns * 16 + l15;
;           const size_t xi = (size_t)row * D + col;
;           const float xv = xin ? xin[xi] : P.out[xi];
;           P.out[xi] = alpha * xv + sc * acc[ms][ns][j];
;         }
	v_mul_f32_e32 v156, v212, v156
	v_fmac_f32_e32 v156, v211, v46
	global_store_dword v132, v156, s[86:87] offset:-4096
	v_mul_f32_e32 v157, v212, v157
	v_fmac_f32_e32 v157, v211, v42
	global_store_dword v132, v157, s[86:87] offset:-4032
	v_mul_f32_e32 v158, v212, v158
	v_fmac_f32_e32 v158, v211, v38
	global_store_dword v132, v158, s[86:87] offset:-3968
	v_mul_f32_e32 v159, v212, v159
	v_fmac_f32_e32 v159, v211, v34
	global_store_dword v132, v159, s[86:87] offset:-3904
	v_mul_f32_e32 v160, v212, v160
	v_fmac_f32_e32 v160, v211, v47
	global_store_dword v132, v160, s[86:87]
	v_mul_f32_e32 v161, v212, v161
	v_fmac_f32_e32 v161, v211, v43
	global_store_dword v132, v161, s[86:87] offset:64
	v_mul_f32_e32 v162, v212, v162
	v_fmac_f32_e32 v162, v211, v39
	global_store_dword v132, v162, s[86:87] offset:128
	v_mul_f32_e32 v163, v212, v163
	v_fmac_f32_e32 v163, v211, v35
	global_store_dword v132, v163, s[86:87] offset:192
	v_mul_f32_e32 v164, v212, v164
	v_fmac_f32_e32 v164, v211, v48
	global_store_dword v133, v164, s[86:87] offset:-4096
	v_mul_f32_e32 v165, v212, v165
	v_fmac_f32_e32 v165, v211, v44
	global_store_dword v133, v165, s[86:87] offset:-4032
	v_mul_f32_e32 v166, v212, v166
	v_fmac_f32_e32 v166, v211, v40
	global_store_dword v133, v166, s[86:87] offset:-3968
	v_mul_f32_e32 v167, v212, v167
	v_fmac_f32_e32 v167, v211, v36
	global_store_dword v133, v167, s[86:87] offset:-3904
	v_mul_f32_e32 v168, v212, v168
	v_fmac_f32_e32 v168, v211, v49
	global_store_dword v133, v168, s[86:87]
	v_mul_f32_e32 v169, v212, v169
	v_fmac_f32_e32 v169, v211, v45
	global_store_dword v133, v169, s[86:87] offset:64
	v_mul_f32_e32 v170, v212, v170
	v_fmac_f32_e32 v170, v211, v41
	global_store_dword v133, v170, s[86:87] offset:128
	v_mul_f32_e32 v171, v212, v171
	v_fmac_f32_e32 v171, v211, v37
	global_store_dword v133, v171, s[86:87] offset:192
	v_add_u32_e32 v132, 0x70000, v138
	v_add_u32_e32 v133, 0x2000, v132
	global_load_dword v156, v132, s[8:9] offset:-4096
	global_load_dword v157, v132, s[8:9] offset:-4032
	global_load_dword v158, v132, s[8:9] offset:-3968
	global_load_dword v159, v132, s[8:9] offset:-3904
	global_load_dword v160, v132, s[8:9]
	global_load_dword v161, v132, s[8:9] offset:64
	global_load_dword v162, v132, s[8:9] offset:128
	global_load_dword v163, v132, s[8:9] offset:192
	global_load_dword v164, v133, s[8:9] offset:-4096
	global_load_dword v165, v133, s[8:9] offset:-4032
	global_load_dword v166, v133, s[8:9] offset:-3968
	global_load_dword v167, v133, s[8:9] offset:-3904
	global_load_dword v168, v133, s[8:9]
	global_load_dword v169, v133, s[8:9] offset:64
	global_load_dword v170, v133, s[8:9] offset:128
	global_load_dword v171, v133, s[8:9] offset:192
	s_waitcnt vmcnt(32)
	v_mul_f32_e32 v140, v212, v140
	v_fmac_f32_e32 v140, v211, v30
	global_store_dword v130, v140, s[86:87] offset:-4096
	v_mul_f32_e32 v141, v212, v141
	v_fmac_f32_e32 v141, v211, v26
	global_store_dword v130, v141, s[86:87] offset:-4032
	v_mul_f32_e32 v142, v212, v142
	v_fmac_f32_e32 v142, v211, v22
	global_store_dword v130, v142, s[86:87] offset:-3968
	v_mul_f32_e32 v143, v212, v143
	v_fmac_f32_e32 v143, v211, v18
	global_store_dword v130, v143, s[86:87] offset:-3904
	v_mul_f32_e32 v144, v212, v144
	v_fmac_f32_e32 v144, v211, v31
	global_store_dword v130, v144, s[86:87]
	v_mul_f32_e32 v145, v212, v145
	v_fmac_f32_e32 v145, v211, v27
	global_store_dword v130, v145, s[86:87] offset:64
	v_mul_f32_e32 v146, v212, v146
	v_fmac_f32_e32 v146, v211, v23
	global_store_dword v130, v146, s[86:87] offset:128
	v_mul_f32_e32 v147, v212, v147
	v_fmac_f32_e32 v147, v211, v19
	global_store_dword v130, v147, s[86:87] offset:192
	v_mul_f32_e32 v148, v212, v148
	v_fmac_f32_e32 v148, v211, v32
	global_store_dword v131, v148, s[86:87] offset:-4096
	v_mul_f32_e32 v149, v212, v149
	v_fmac_f32_e32 v149, v211, v28
	global_store_dword v131, v149, s[86:87] offset:-4032
	v_mul_f32_e32 v150, v212, v150
	v_fmac_f32_e32 v150, v211, v24
	global_store_dword v131, v150, s[86:87] offset:-3968
	v_mul_f32_e32 v151, v212, v151
	v_fmac_f32_e32 v151, v211, v20
	global_store_dword v131, v151, s[86:87] offset:-3904
	v_mul_f32_e32 v152, v212, v152
	v_fmac_f32_e32 v152, v211, v33
	global_store_dword v131, v152, s[86:87]
	v_mul_f32_e32 v153, v212, v153
	v_fmac_f32_e32 v153, v211, v29
	global_store_dword v131, v153, s[86:87] offset:64
	v_mul_f32_e32 v154, v212, v154
	v_fmac_f32_e32 v154, v211, v25
	global_store_dword v131, v154, s[86:87] offset:128
	v_mul_f32_e32 v155, v212, v155
	v_fmac_f32_e32 v155, v211, v21
	global_store_dword v131, v155, s[86:87] offset:192
	s_waitcnt vmcnt(16)
	v_mul_f32_e32 v156, v212, v156
	v_fmac_f32_e32 v156, v211, v14
	global_store_dword v132, v156, s[86:87] offset:-4096
	v_mul_f32_e32 v157, v212, v157
	v_fmac_f32_e32 v157, v211, v10
	global_store_dword v132, v157, s[86:87] offset:-4032
	v_mul_f32_e32 v158, v212, v158
	v_fmac_f32_e32 v158, v211, v6
	global_store_dword v132, v158, s[86:87] offset:-3968
	v_mul_f32_e32 v159, v212, v159
	v_fmac_f32_e32 v159, v211, v2
	global_store_dword v132, v159, s[86:87] offset:-3904
	v_mul_f32_e32 v160, v212, v160
	v_fmac_f32_e32 v160, v211, v15
	global_store_dword v132, v160, s[86:87]
	v_mul_f32_e32 v161, v212, v161
	v_fmac_f32_e32 v161, v211, v11
	global_store_dword v132, v161, s[86:87] offset:64
	v_mul_f32_e32 v162, v212, v162
	v_fmac_f32_e32 v162, v211, v7
	global_store_dword v132, v162, s[86:87] offset:128
	v_mul_f32_e32 v163, v212, v163
	v_fmac_f32_e32 v163, v211, v3
	global_store_dword v132, v163, s[86:87] offset:192
	v_mul_f32_e32 v164, v212, v164
	v_fmac_f32_e32 v164, v211, v16
	global_store_dword v133, v164, s[86:87] offset:-4096
	v_mul_f32_e32 v165, v212, v165
	v_fmac_f32_e32 v165, v211, v12
	global_store_dword v133, v165, s[86:87] offset:-4032
	v_mul_f32_e32 v166, v212, v166
	v_fmac_f32_e32 v166, v211, v8
	global_store_dword v133, v166, s[86:87] offset:-3968
	v_mul_f32_e32 v167, v212, v167
	v_fmac_f32_e32 v167, v211, v4
	global_store_dword v133, v167, s[86:87] offset:-3904
	v_mul_f32_e32 v168, v212, v168
	v_fmac_f32_e32 v168, v211, v17
	global_store_dword v133, v168, s[86:87]
	v_mul_f32_e32 v169, v212, v169
	v_fmac_f32_e32 v169, v211, v13
	global_store_dword v133, v169, s[86:87] offset:64
	v_mul_f32_e32 v170, v212, v170
	v_fmac_f32_e32 v170, v211, v9
	global_store_dword v133, v170, s[86:87] offset:128
	v_mul_f32_e32 v171, v212, v171
	v_fmac_f32_e32 v171, v211, v5
	global_store_dword v133, v171, s[86:87] offset:192
	s_and_b64 vcc, exec, s[12:13]
	s_cbranch_vccnz .LBB0_2285
	s_branch .LBB0_2257
